# relax first-iteration vmcnt after epilogue stores in 3 RowNorm GEMMs; drop vmcnt(0) before row-stat prefetch
# speedup vs baseline: 1.0045x; 1.0045x over previous
; #define PG8_LAS __attribute__((address_space(3)))
; #define LAS __attribute__((address_space(3)))
; __global__ void __launch_bounds__(512, 2) fwd_megakernel(Args a) {
;     extern __shared__ __attribute__((aligned(16))) unsigned char lds[];
;     cg::grid_group grid = cg::this_grid();
;     const int wv0 = __builtin_amdgcn_readfirstlane((int)threadIdx.x >> 6);
;     Frame F; F.lds = lds; F.tid = threadIdx.x; F.lane = F.tid & 63; F.wave = __builtin_amdgcn_readfirstlane(F.tid >> 6); F.G = gridDim.x; F.bid = blockIdx.x;
;     PG8_LAS unsigned char* glds = (PG8_LAS unsigned char*)lds;
;     {
;         int z = 0; asm volatile("" : "+s"(z));
;         unsigned* bw = (unsigned*)AIN(24);
;         volatile LAS unsigned* st = (volatile LAS unsigned*)(glds + (LDS_BYTES - 16));
;         if (threadIdx.x < 2) st[threadIdx.x] = 0u;
;         __syncthreads();
;         (void)xcd_barrier_post(bw, st);
;     }
_Z14fwd_megakernel4Args:
	s_mov_b32 s81, s2
	s_mov_b32 s98, 0
	s_add_u32 s2, s0, 0xd0
	s_addc_u32 s3, s1, 0
	v_and_b32_e32 v1, 0x3ff, v0
	v_writelane_b32 v254, s2, 0
	v_readfirstlane_b32 s6, v1
	v_cmp_gt_u32_e32 vcc, 2, v1
	v_writelane_b32 v254, s3, 1
	s_load_dwordx2 s[2:3], s[0:1], 0xd0
	s_waitcnt lgkmcnt(0)
	v_writelane_b32 v254, s2, 2
	s_nop 1
	v_writelane_b32 v254, s3, 3
	s_mov_b32 s2, 0
	s_ashr_i32 s3, s2, 31
	s_lshl_b64 s[2:3], s[2:3], 3
	s_add_u32 s2, s0, s2
	v_writelane_b32 v254, s0, 4
	s_addc_u32 s3, s1, s3
	s_nop 0
	v_writelane_b32 v254, s1, 5
	s_load_dwordx2 s[0:1], s[2:3], 0xc0
	s_and_saveexec_b64 s[2:3], vcc
	v_lshl_add_u32 v2, v1, 2, 0
	v_add_u32_e32 v2, 0x23ff0, v2
	v_mov_b32_e32 v3, 0
	ds_write_b32 v2, v3
	s_or_b64 exec, exec, s[2:3]
	s_waitcnt lgkmcnt(0)
	s_barrier
	s_getreg_b32 s7, hwreg(HW_REG_XCC_ID, 0, 4)
	v_cmp_eq_u32_e32 vcc, 0, v1
	s_and_saveexec_b64 s[2:3], vcc
	s_cbranch_execz .LBB0_5
	s_mov_b64 s[4:5], exec
	v_mbcnt_lo_u32_b32 v2, s4, 0
	v_mbcnt_hi_u32_b32 v2, s5, v2
	v_cmp_eq_u32_e32 vcc, 0, v2
	s_and_b64 s[8:9], exec, vcc
	s_mov_b64 exec, s[8:9]
	s_cbranch_execz .LBB0_5
	s_lshl_b32 s7, s7, 8
	s_and_b32 s7, s7, 0xf00
	s_bcnt1_i32_b64 s4, s[4:5]
	v_mov_b32_e32 v2, s7
	v_mov_b32_e32 v3, s4
	global_atomic_add v2, v3, s[0:1] offset:1024

; __device__ __forceinline__ int lane_id_() { return (int)__builtin_amdgcn_mbcnt_hi(~0u, __builtin_amdgcn_mbcnt_lo(~0u, 0u)); }
; __global__ void __launch_bounds__(512, 2) fwd_megakernel(Args a) {
;     ...
;     for (int ph = a.ph_lo; ph < a.ph_hi; ++ph) {
;       const int sub_ = ph & 7; if (sub_ == 4) continue;
;       {
;         { int t_ = wv0 * 64 + lane_id_(); asm volatile("" : "+v"(t_)); F.tid = t_; F.lane = t_ & 63; F.wave = wv0; }
;         { int g_ = (int)gridDim.x, b_ = (int)blockIdx.x; asm volatile("" : "+s"(g_), "+s"(b_)); F.G = g_; F.bid = b_; }
;         int z = 0; asm volatile("" : "+s"(z));
;         unsigned char* ws = (unsigned char*)AIN(24);
;         bf16* WA = (bf16*)(ws + WS_WA); bf16* WB = (bf16*)(ws + WS_WB); bf16* WUP = (bf16*)(ws + WS_WUP); bf16* WDN = (bf16*)(ws + WS_WDN);
;         bf16* XB = (bf16*)(ws + WS_XB); float* DT = (float*)(ws + WS_DT); bf16* BIG = (bf16*)(ws + WS_BIG);
;         bf16* OB = (bf16*)(ws + WS_O); bf16* CK = (bf16*)(ws + WS_CK); bf16* CV = (bf16*)(ws + WS_CV);
;         float* X = (float*)AIN(23);
;         float* ST0 = (float*)(ws + WS_ST0); float* ST1 = (float*)(ws + WS_ST1);
;         const int L = ph >> 3, sub = ph & 7, li = L >> 1; const bool ssm = (L & 1);
;         if (sub == 0) {
.LBB0_8:
	s_mov_b32 s98, 0
	s_and_b32 s80, s24, 7
	s_cmp_eq_u32 s80, 4
	s_cbranch_scc1 .LBB0_7
	v_mov_b32_e32 v176, v233
	v_readlane_b32 s0, v254, 2
	s_mov_b32 s2, s81
	v_readlane_b32 s1, v254, 3
	v_writelane_b32 v254, s2, 38
	v_and_b32_e32 v177, 63, v176
	s_nop 0
	v_writelane_b32 v254, s3, 39
	v_writelane_b32 v254, s0, 40
	s_nop 1
	v_writelane_b32 v254, s1, 41
	s_mov_b32 s0, s51
	s_ashr_i32 s1, s0, 31
	s_lshl_b64 s[0:1], s[0:1], 3
	v_readlane_b32 s2, v254, 4
	v_readlane_b32 s3, v254, 5
	s_add_u32 s88, s2, s0
	s_addc_u32 s89, s3, s1
	s_load_dwordx4 s[0:3], s[88:89], 0xb8
	s_waitcnt lgkmcnt(0)
	s_add_u32 s0, s2, 0xe00000
	s_addc_u32 s1, s3, 0
	v_writelane_b32 v254, s0, 42
	s_nop 1
	v_writelane_b32 v254, s1, 43
	s_add_u32 s0, s2, 0x1200000
	s_addc_u32 s1, s3, 0
	v_writelane_b32 v254, s0, 44
	s_nop 1
	v_writelane_b32 v254, s1, 45
	s_add_u32 s0, s2, 0x1a00000
	s_addc_u32 s1, s3, 0
	s_add_u32 s94, s2, 0x2200000
	s_addc_u32 s95, s3, 0
	s_add_u32 s74, s2, 0xaf00000
	v_writelane_b32 v254, s0, 46
	s_addc_u32 s75, s3, 0
	s_nop 0
	v_writelane_b32 v254, s1, 47
	s_add_u32 s0, s2, 0x23b00000
	s_addc_u32 s1, s3, 0
	v_writelane_b32 v254, s0, 48
	s_nop 1
	v_writelane_b32 v254, s1, 49
	s_add_u32 s0, s2, 0x2bf00000
	s_addc_u32 s1, s3, 0
	v_writelane_b32 v254, s0, 50
	s_nop 1
	v_writelane_b32 v254, s1, 51
	s_add_u32 s0, s2, 0x3c700000
	s_addc_u32 s1, s3, 0
	v_writelane_b32 v254, s0, 52
	s_nop 1
	v_writelane_b32 v254, s1, 53
	s_ashr_i32 s0, s24, 3
	v_writelane_b32 v254, s0, 54
	s_bitcmp1_b32 s24, 3
	s_nop 0
	v_writelane_b32 v254, s1, 55
	s_cselect_b64 s[0:1], -1, 0
	v_writelane_b32 v254, s0, 56
	s_cmp_lt_i32 s80, 3
	s_nop 0
	v_writelane_b32 v254, s1, 57
	v_writelane_b32 v254, s24, 58
	s_mov_b64 s[0:1], -1
	s_nop 0
	v_writelane_b32 v254, s25, 59
	s_cbranch_scc1 .LBB0_392
	s_load_dwordx4 s[0:3], s[88:89], 0xb8
	s_mov_b64 s[4:5], -1
	s_mov_b64 s[82:83], 0
	s_waitcnt lgkmcnt(0)
	s_add_u32 s0, s2, 0x3c940000
	s_addc_u32 s1, s3, 0
	v_writelane_b32 v254, s0, 60
	s_cmp_lt_i32 s80, 5
	s_mov_b64 s[2:3], 0
	v_writelane_b32 v254, s1, 61
	s_cbranch_scc0 .LBB0_14
	s_and_b64 vcc, exec, s[4:5]
	s_cbranch_vccnz .LBB0_107

; #define PG8_STAGE(bufoff, gbase, voff) do { _Pragma("unroll") for (int _i = 0; _i < 2; ++_i) \
;         __builtin_amdgcn_global_load_lds((const unsigned*)((const char*)(gbase) + (voff)[_i]), (PG8_LAS unsigned*)(lds + (bufoff) + ldsw + _i * 8192), 16, 0, 0); } while (0)
; #define PG8_LDA(dst, b, h) do { _Pragma("unroll") for (int m = 0; m < 4; ++m) _Pragma("unroll") for (int k = 0; k < 2; ++k) dst[m][k] = *(const PG8_LAS bf16x8*)(lds + PG8_SA(b, h) + aoff + m * 2048 + k * 1024); } while (0)
; #define PG8_LDB(dst, b, h) do { _Pragma("unroll") for (int n = 0; n < 2; ++n) _Pragma("unroll") for (int k = 0; k < 2; ++k) dst[n][k] = *(const PG8_LAS bf16x8*)(lds + PG8_SB(b, h) + boff + n * 2048 + k * 1024); } while (0)
; #define PG8_MMA(ai, bj, At, Bt) do { __builtin_amdgcn_s_setprio(1); _Pragma("unroll") for (int m = 0; m < 4; ++m) _Pragma("unroll") for (int n = 0; n < 2; ++n) _Pragma("unroll") for (int k = 0; k < 2; ++k) \
;         acc[ai][bj][m][n] = __builtin_amdgcn_mfma_f32_16x16x32_bf16(Bt[n][k], At[m][k], acc[ai][bj][m][n], 0, 0, 0); __builtin_amdgcn_s_setprio(0); } while (0)
; #define PG8_WAIT_V(n) asm volatile("s_waitcnt vmcnt(" #n ")" ::: "memory")
; #define PG8_WAIT_L(n) asm volatile("s_waitcnt lgkmcnt(" #n ")" ::: "memory")
; #define PG8_BAR __builtin_amdgcn_s_barrier()
; template <class Epi, class Sched, bool ALIGN_EPI = false, bool SP2 = false>
; __device__ __forceinline__ void gemm_phase(PG8_LAS unsigned char* lds, const Gemm g, const Sched& S, const Epi& E, const int wave_id) {
;     ...
;             const char* a1 = cA + (size_t)(t + 1) * kstep;
;             const char* a2 = last ? nA : cA + (size_t)(t + 2) * kstep; const char* b2 = last ? nB : cB + (size_t)(t + 2) * kstep;
;             const char* a3 = a2 + kstep; const char* b3 = b2 + kstep;
;             if (last && has_next) S.a_ready(nxt);
;             if constexpr (SP2) {
;             PG8_LDB(B0, 0, 0); PG8_LDB(B1, 0, 1); PG8_SCHED; PG8_LDA(At, 0, 0); PG8_STAGE(PG8_SA(1, 1), a1 + hstepA, voffA);
;             PG8_WAIT_V(8); PG8_WAIT_L(0); PG8_BAR; PG8_MMA(0, 0, At, B0); PG8_MMA(0, 1, At, B1); PG8_BAR; PG8_SCHED;
;             PG8_LDA(At, 0, 1); PG8_STAGE(PG8_SB(0, 0), b2, voffB); PG8_STAGE(PG8_SB(0, 1), b2 + hstepB, voffB); PG8_STAGE(PG8_SA(0, 0), a2, voffA);
;             PG8_WAIT_V(8); PG8_WAIT_L(0); PG8_BAR; PG8_MMA(1, 0, At, B0); PG8_MMA(1, 1, At, B1); PG8_BAR; PG8_SCHED;
.LBB0_90:
	s_add_u32 s10, s8, 0xfffc0080
	s_addc_u32 s11, s9, -1
	s_add_i32 s37, 0, 0x10000
	s_cmp_eq_u32 s5, 12
	s_cselect_b32 s31, s21, s11
	s_cselect_b32 s30, vcc_lo, s10
	v_add_u32_e32 v0, s37, v203
	s_cselect_b32 s29, s19, s4
	s_cselect_b32 s28, vcc_hi, s38
	s_add_i32 s39, 0, 0x14000
	ds_read_b128 v[138:141], v0
	ds_read_b128 v[142:145], v0 offset:1024
	ds_read_b128 v[146:149], v0 offset:2048
	ds_read_b128 v[150:153], v0 offset:3072
	v_add_u32_e32 v0, s39, v203
	ds_read_b128 v[154:157], v0
	ds_read_b128 v[158:161], v0 offset:1024
	ds_read_b128 v[162:165], v0 offset:2048
	ds_read_b128 v[166:169], v0 offset:3072
	v_lshl_add_u64 v[240:241], s[8:9], 0, v[186:187]
	s_add_i32 m0, s27, 0xc000
	ds_read_b128 v[190:193], v208
	ds_read_b128 v[194:197], v208 offset:1024
	ds_read_b128 v[198:201], v208 offset:2048
	ds_read_b128 v[210:213], v208 offset:3072
	ds_read_b128 v[214:217], v208 offset:4096
	ds_read_b128 v[218:221], v208 offset:5120
	ds_read_b128 v[222:225], v208 offset:6144
	ds_read_b128 v[234:237], v208 offset:7168
	global_load_lds_dwordx4 v[240:241], off
	v_lshl_add_u64 v[240:241], s[8:9], 0, v[188:189]
	s_add_i32 m0, s27, 0xe000
	s_nop 0
	global_load_lds_dwordx4 v[240:241], off
	s_waitcnt vmcnt(24)
	s_cmp_eq_u32 s98, 1
	s_cbranch_scc1 .Lrw_1
	s_waitcnt vmcnt(8)
.Lrw_1:
	s_waitcnt lgkmcnt(0)
	s_barrier
	s_setprio 1
	s_waitcnt lgkmcnt(0)
	v_mfma_f32_16x16x32_bf16 v[134:137], v[138:141], v[190:193], v[134:137]
	v_mfma_f32_16x16x32_bf16 v[130:133], v[146:149], v[190:193], v[130:133]
	v_mfma_f32_16x16x32_bf16 v[118:121], v[138:141], v[198:201], v[118:121]
	v_mfma_f32_16x16x32_bf16 v[114:117], v[146:149], v[198:201], v[114:117]
	v_mfma_f32_16x16x32_bf16 v[102:105], v[138:141], v[214:217], v[102:105]
	v_mfma_f32_16x16x32_bf16 v[98:101], v[146:149], v[214:217], v[98:101]
	v_mfma_f32_16x16x32_bf16 v[86:89], v[138:141], v[222:225], v[86:89]
	v_mfma_f32_16x16x32_bf16 v[82:85], v[146:149], v[222:225], v[82:85]
	v_mfma_f32_16x16x32_bf16 v[134:137], v[142:145], v[194:197], v[134:137]
	v_mfma_f32_16x16x32_bf16 v[130:133], v[150:153], v[194:197], v[130:133]
	v_mfma_f32_16x16x32_bf16 v[118:121], v[142:145], v[210:213], v[118:121]
	v_mfma_f32_16x16x32_bf16 v[114:117], v[150:153], v[210:213], v[114:117]
	v_mfma_f32_16x16x32_bf16 v[102:105], v[142:145], v[218:221], v[102:105]
	v_mfma_f32_16x16x32_bf16 v[98:101], v[150:153], v[218:221], v[98:101]
	v_mfma_f32_16x16x32_bf16 v[86:89], v[142:145], v[234:237], v[86:89]
	v_mfma_f32_16x16x32_bf16 v[82:85], v[150:153], v[234:237], v[82:85]
	s_setprio 0
	s_setprio 1
	v_mfma_f32_16x16x32_bf16 v[126:129], v[154:157], v[190:193], v[126:129]
	v_mfma_f32_16x16x32_bf16 v[122:125], v[162:165], v[190:193], v[122:125]
	v_mfma_f32_16x16x32_bf16 v[110:113], v[154:157], v[198:201], v[110:113]
	v_mfma_f32_16x16x32_bf16 v[106:109], v[162:165], v[198:201], v[106:109]
	v_mfma_f32_16x16x32_bf16 v[94:97], v[154:157], v[214:217], v[94:97]
	v_mfma_f32_16x16x32_bf16 v[90:93], v[162:165], v[214:217], v[90:93]
	v_mfma_f32_16x16x32_bf16 v[78:81], v[154:157], v[222:225], v[78:81]
	v_mfma_f32_16x16x32_bf16 v[74:77], v[162:165], v[222:225], v[74:77]
	v_mfma_f32_16x16x32_bf16 v[126:129], v[158:161], v[194:197], v[126:129]
	v_mfma_f32_16x16x32_bf16 v[122:125], v[166:169], v[194:197], v[122:125]
	v_mfma_f32_16x16x32_bf16 v[110:113], v[158:161], v[210:213], v[110:113]
	v_mfma_f32_16x16x32_bf16 v[106:109], v[166:169], v[210:213], v[106:109]
	v_mfma_f32_16x16x32_bf16 v[94:97], v[158:161], v[218:221], v[94:97]
	v_mfma_f32_16x16x32_bf16 v[90:93], v[166:169], v[218:221], v[90:93]
	v_mfma_f32_16x16x32_bf16 v[78:81], v[158:161], v[234:237], v[78:81]
	v_mfma_f32_16x16x32_bf16 v[74:77], v[166:169], v[234:237], v[74:77]
	s_setprio 0
	s_barrier
	s_add_i32 s10, s37, s15
	v_lshl_add_u64 v[240:241], s[28:29], 0, v[180:181]
	s_mov_b32 m0, s10
	ds_read_b128 v[190:193], v208 offset:16384
	ds_read_b128 v[194:197], v208 offset:17408
	ds_read_b128 v[198:201], v208 offset:18432
	ds_read_b128 v[210:213], v208 offset:19456
	ds_read_b128 v[214:217], v208 offset:20480
	ds_read_b128 v[218:221], v208 offset:21504
	ds_read_b128 v[222:225], v208 offset:22528
	ds_read_b128 v[234:237], v208 offset:23552
	global_load_lds_dwordx4 v[240:241], off
	s_add_i32 m0, s10, 0x2000
	s_add_u32 s10, s28, 0x40000
	v_lshl_add_u64 v[242:243], s[28:29], 0, v[184:185]
	s_addc_u32 s11, s29, 0
	s_add_i32 s37, s39, s15
	global_load_lds_dwordx4 v[242:243], off
	v_lshl_add_u64 v[244:245], s[10:11], 0, v[180:181]
	s_mov_b32 m0, s37
	v_lshl_add_u64 v[246:247], s[30:31], 0, v[182:183]
	global_load_lds_dwordx4 v[244:245], off
	v_lshl_add_u64 v[244:245], s[10:11], 0, v[184:185]
	s_add_i32 m0, s37, 0x2000
	s_nop 0
	global_load_lds_dwordx4 v[244:245], off
	v_lshl_add_u64 v[244:245], s[30:31], 0, v[178:179]
	s_mov_b32 m0, s27
	s_nop 0
	global_load_lds_dwordx4 v[244:245], off
	s_mov_b32 m0, s34
	s_nop 0
	global_load_lds_dwordx4 v[246:247], off
	s_waitcnt vmcnt(24)
	s_cmp_eq_u32 s98, 1
	s_cbranch_scc1 .Lrw_2
	s_waitcnt vmcnt(8)
; #define PG8_STAGE(bufoff, gbase, voff) do { _Pragma("unroll") for (int _i = 0; _i < 2; ++_i) \
;         __builtin_amdgcn_global_load_lds((const unsigned*)((const char*)(gbase) + (voff)[_i]), (PG8_LAS unsigned*)(lds + (bufoff) + ldsw + _i * 8192), 16, 0, 0); } while (0)
; #define PG8_LDA(dst, b, h) do { _Pragma("unroll") for (int m = 0; m < 4; ++m) _Pragma("unroll") for (int k = 0; k < 2; ++k) dst[m][k] = *(const PG8_LAS bf16x8*)(lds + PG8_SA(b, h) + aoff + m * 2048 + k * 1024); } while (0)
; #define PG8_LDB(dst, b, h) do { _Pragma("unroll") for (int n = 0; n < 2; ++n) _Pragma("unroll") for (int k = 0; k < 2; ++k) dst[n][k] = *(const PG8_LAS bf16x8*)(lds + PG8_SB(b, h) + boff + n * 2048 + k * 1024); } while (0)
; #define PG8_MMA(ai, bj, At, Bt) do { __builtin_amdgcn_s_setprio(1); _Pragma("unroll") for (int m = 0; m < 4; ++m) _Pragma("unroll") for (int n = 0; n < 2; ++n) _Pragma("unroll") for (int k = 0; k < 2; ++k) \
;         acc[ai][bj][m][n] = __builtin_amdgcn_mfma_f32_16x16x32_bf16(Bt[n][k], At[m][k], acc[ai][bj][m][n], 0, 0, 0); __builtin_amdgcn_s_setprio(0); } while (0)
; #define PG8_WAIT_V(n) asm volatile("s_waitcnt vmcnt(" #n ")" ::: "memory")
; #define PG8_WAIT_L(n) asm volatile("s_waitcnt lgkmcnt(" #n ")" ::: "memory")
; #define PG8_BAR __builtin_amdgcn_s_barrier()
; #define PG8_SCHED __builtin_amdgcn_sched_barrier(0)
; template <class Epi, class Sched, bool ALIGN_EPI = false, bool SP2 = false>
; __device__ __forceinline__ void gemm_phase(PG8_LAS unsigned char* lds, const Gemm g, const Sched& S, const Epi& E, const int wave_id) {
;     ...
;             PG8_WAIT_V(8); PG8_WAIT_L(0); PG8_BAR; PG8_MMA(1, 0, At, B0); PG8_MMA(1, 1, At, B1); PG8_BAR; PG8_SCHED;
;             PG8_LDB(B0, 1, 0); PG8_LDB(B1, 1, 1); PG8_SCHED; PG8_LDA(At, 1, 0); PG8_STAGE(PG8_SA(0, 1), a2 + hstepA, voffA);
;             PG8_WAIT_V(8); PG8_WAIT_L(0); PG8_BAR; PG8_MMA(0, 0, At, B0); PG8_MMA(0, 1, At, B1); PG8_BAR; PG8_SCHED;
.Lrw_2:
	s_mov_b32 s98, 0
	s_waitcnt lgkmcnt(0)
	s_barrier
	s_setprio 1
	s_waitcnt lgkmcnt(0)
	v_mfma_f32_16x16x32_bf16 v[70:73], v[138:141], v[190:193], v[70:73]
	v_mfma_f32_16x16x32_bf16 v[66:69], v[146:149], v[190:193], v[66:69]
	v_mfma_f32_16x16x32_bf16 v[54:57], v[138:141], v[198:201], v[54:57]
	v_mfma_f32_16x16x32_bf16 v[50:53], v[146:149], v[198:201], v[50:53]
	v_mfma_f32_16x16x32_bf16 v[38:41], v[138:141], v[214:217], v[38:41]
	v_mfma_f32_16x16x32_bf16 v[34:37], v[146:149], v[214:217], v[34:37]
	v_mfma_f32_16x16x32_bf16 v[22:25], v[138:141], v[222:225], v[22:25]
	v_mfma_f32_16x16x32_bf16 v[18:21], v[146:149], v[222:225], v[18:21]
	v_mfma_f32_16x16x32_bf16 v[70:73], v[142:145], v[194:197], v[70:73]
	v_mfma_f32_16x16x32_bf16 v[66:69], v[150:153], v[194:197], v[66:69]
	v_mfma_f32_16x16x32_bf16 v[54:57], v[142:145], v[210:213], v[54:57]
	v_mfma_f32_16x16x32_bf16 v[50:53], v[150:153], v[210:213], v[50:53]
	v_mfma_f32_16x16x32_bf16 v[38:41], v[142:145], v[218:221], v[38:41]
	v_mfma_f32_16x16x32_bf16 v[34:37], v[150:153], v[218:221], v[34:37]
	v_mfma_f32_16x16x32_bf16 v[22:25], v[142:145], v[234:237], v[22:25]
	v_mfma_f32_16x16x32_bf16 v[18:21], v[150:153], v[234:237], v[18:21]
	s_setprio 0
	s_setprio 1
	v_mfma_f32_16x16x32_bf16 v[62:65], v[154:157], v[190:193], v[62:65]
	v_mfma_f32_16x16x32_bf16 v[58:61], v[162:165], v[190:193], v[58:61]
	v_mfma_f32_16x16x32_bf16 v[46:49], v[154:157], v[198:201], v[46:49]
	v_mfma_f32_16x16x32_bf16 v[42:45], v[162:165], v[198:201], v[42:45]
	v_mfma_f32_16x16x32_bf16 v[30:33], v[154:157], v[214:217], v[30:33]
	v_mfma_f32_16x16x32_bf16 v[26:29], v[162:165], v[214:217], v[26:29]
	v_mfma_f32_16x16x32_bf16 v[14:17], v[154:157], v[222:225], v[14:17]
	v_mfma_f32_16x16x32_bf16 v[10:13], v[162:165], v[222:225], v[10:13]
	v_mfma_f32_16x16x32_bf16 v[62:65], v[158:161], v[194:197], v[62:65]
	v_mfma_f32_16x16x32_bf16 v[58:61], v[166:169], v[194:197], v[58:61]
	v_mfma_f32_16x16x32_bf16 v[46:49], v[158:161], v[210:213], v[46:49]
	v_mfma_f32_16x16x32_bf16 v[42:45], v[166:169], v[210:213], v[42:45]
	v_mfma_f32_16x16x32_bf16 v[30:33], v[158:161], v[218:221], v[30:33]
	v_mfma_f32_16x16x32_bf16 v[26:29], v[166:169], v[218:221], v[26:29]
	v_mfma_f32_16x16x32_bf16 v[14:17], v[158:161], v[234:237], v[14:17]
	v_mfma_f32_16x16x32_bf16 v[10:13], v[166:169], v[234:237], v[10:13]
	s_setprio 0
	s_barrier
	s_add_i32 s37, 0, 0x18000
	v_add_u32_e32 v0, s37, v203
	s_add_i32 s39, 0, 0x1c000
	ds_read_b128 v[138:141], v0
	ds_read_b128 v[142:145], v0 offset:1024
	ds_read_b128 v[146:149], v0 offset:2048
	ds_read_b128 v[150:153], v0 offset:3072
	v_add_u32_e32 v0, s39, v203
	ds_read_b128 v[154:157], v0
	ds_read_b128 v[158:161], v0 offset:1024
	ds_read_b128 v[162:165], v0 offset:2048
	ds_read_b128 v[166:169], v0 offset:3072
	s_add_u32 s10, s30, 0x40000
	s_addc_u32 s11, s31, 0
	s_mov_b32 m0, s35
	v_lshl_add_u64 v[248:249], s[10:11], 0, v[178:179]
	ds_read_b128 v[190:193], v208 offset:32768
	ds_read_b128 v[194:197], v208 offset:33792
	ds_read_b128 v[198:201], v208 offset:34816
	ds_read_b128 v[210:213], v208 offset:35840
	ds_read_b128 v[214:217], v208 offset:36864
	ds_read_b128 v[218:221], v208 offset:37888
	ds_read_b128 v[222:225], v208 offset:38912
	ds_read_b128 v[234:237], v208 offset:39936
	global_load_lds_dwordx4 v[248:249], off
	v_lshl_add_u64 v[248:249], s[10:11], 0, v[182:183]
	s_mov_b32 m0, s36
	s_nop 0
	global_load_lds_dwordx4 v[248:249], off
	s_waitcnt vmcnt(8)
	s_waitcnt lgkmcnt(0)
	s_barrier
	s_setprio 1
	s_waitcnt lgkmcnt(0)
	v_mfma_f32_16x16x32_bf16 v[134:137], v[138:141], v[190:193], v[134:137]
	v_mfma_f32_16x16x32_bf16 v[130:133], v[146:149], v[190:193], v[130:133]
	v_mfma_f32_16x16x32_bf16 v[118:121], v[138:141], v[198:201], v[118:121]
	v_mfma_f32_16x16x32_bf16 v[114:117], v[146:149], v[198:201], v[114:117]
	v_mfma_f32_16x16x32_bf16 v[102:105], v[138:141], v[214:217], v[102:105]
	v_mfma_f32_16x16x32_bf16 v[98:101], v[146:149], v[214:217], v[98:101]
	v_mfma_f32_16x16x32_bf16 v[86:89], v[138:141], v[222:225], v[86:89]
	v_mfma_f32_16x16x32_bf16 v[82:85], v[146:149], v[222:225], v[82:85]
	v_mfma_f32_16x16x32_bf16 v[134:137], v[142:145], v[194:197], v[134:137]
	v_mfma_f32_16x16x32_bf16 v[130:133], v[150:153], v[194:197], v[130:133]
	v_mfma_f32_16x16x32_bf16 v[118:121], v[142:145], v[210:213], v[118:121]
	v_mfma_f32_16x16x32_bf16 v[114:117], v[150:153], v[210:213], v[114:117]
	v_mfma_f32_16x16x32_bf16 v[102:105], v[142:145], v[218:221], v[102:105]
	v_mfma_f32_16x16x32_bf16 v[98:101], v[150:153], v[218:221], v[98:101]
	v_mfma_f32_16x16x32_bf16 v[86:89], v[142:145], v[234:237], v[86:89]
	v_mfma_f32_16x16x32_bf16 v[82:85], v[150:153], v[234:237], v[82:85]
	s_setprio 0
	s_setprio 1
	v_mfma_f32_16x16x32_bf16 v[126:129], v[154:157], v[190:193], v[126:129]
	v_mfma_f32_16x16x32_bf16 v[122:125], v[162:165], v[190:193], v[122:125]
	v_mfma_f32_16x16x32_bf16 v[110:113], v[154:157], v[198:201], v[110:113]
	v_mfma_f32_16x16x32_bf16 v[106:109], v[162:165], v[198:201], v[106:109]
	v_mfma_f32_16x16x32_bf16 v[94:97], v[154:157], v[214:217], v[94:97]
	v_mfma_f32_16x16x32_bf16 v[90:93], v[162:165], v[214:217], v[90:93]
	v_mfma_f32_16x16x32_bf16 v[78:81], v[154:157], v[222:225], v[78:81]
	v_mfma_f32_16x16x32_bf16 v[74:77], v[162:165], v[222:225], v[74:77]
	v_mfma_f32_16x16x32_bf16 v[126:129], v[158:161], v[194:197], v[126:129]
	v_mfma_f32_16x16x32_bf16 v[122:125], v[166:169], v[194:197], v[122:125]
	v_mfma_f32_16x16x32_bf16 v[110:113], v[158:161], v[210:213], v[110:113]
	v_mfma_f32_16x16x32_bf16 v[106:109], v[166:169], v[210:213], v[106:109]
	v_mfma_f32_16x16x32_bf16 v[94:97], v[158:161], v[218:221], v[94:97]
	v_mfma_f32_16x16x32_bf16 v[90:93], v[166:169], v[218:221], v[90:93]
	v_mfma_f32_16x16x32_bf16 v[78:81], v[158:161], v[234:237], v[78:81]
	v_mfma_f32_16x16x32_bf16 v[74:77], v[166:169], v[234:237], v[74:77]
	s_setprio 0
	s_barrier
; #define PG8_STAGE(bufoff, gbase, voff) do { _Pragma("unroll") for (int _i = 0; _i < 2; ++_i) \
;         __builtin_amdgcn_global_load_lds((const unsigned*)((const char*)(gbase) + (voff)[_i]), (PG8_LAS unsigned*)(lds + (bufoff) + ldsw + _i * 8192), 16, 0, 0); } while (0)
; #define PG8_LDA(dst, b, h) do { _Pragma("unroll") for (int m = 0; m < 4; ++m) _Pragma("unroll") for (int k = 0; k < 2; ++k) dst[m][k] = *(const PG8_LAS bf16x8*)(lds + PG8_SA(b, h) + aoff + m * 2048 + k * 1024); } while (0)
; #define PG8_MMA(ai, bj, At, Bt) do { __builtin_amdgcn_s_setprio(1); _Pragma("unroll") for (int m = 0; m < 4; ++m) _Pragma("unroll") for (int n = 0; n < 2; ++n) _Pragma("unroll") for (int k = 0; k < 2; ++k) \
;         acc[ai][bj][m][n] = __builtin_amdgcn_mfma_f32_16x16x32_bf16(Bt[n][k], At[m][k], acc[ai][bj][m][n], 0, 0, 0); __builtin_amdgcn_s_setprio(0); } while (0)
; #define PG8_WAIT_V(n) asm volatile("s_waitcnt vmcnt(" #n ")" ::: "memory")
; #define PG8_WAIT_L(n) asm volatile("s_waitcnt lgkmcnt(" #n ")" ::: "memory")
; #define PG8_BAR __builtin_amdgcn_s_barrier()
; #define PG8_SCHED __builtin_amdgcn_sched_barrier(0)
; template <class Epi, class Sched, bool ALIGN_EPI = false, bool SP2 = false>
; __device__ __forceinline__ void gemm_phase(PG8_LAS unsigned char* lds, const Gemm g, const Sched& S, const Epi& E, const int wave_id) {
;     ...
;         for (int t = 0; t < nt; t += 2) {
;             const bool last = (t == nt - 2);
;     ...
;             PG8_LDA(At, 1, 1); PG8_STAGE(PG8_SB(1, 0), b3, voffB); PG8_STAGE(PG8_SB(1, 1), b3 + hstepB, voffB); PG8_STAGE(PG8_SA(1, 0), a3, voffA);
;             PG8_WAIT_V(8); PG8_WAIT_L(0); PG8_BAR; PG8_MMA(1, 0, At, B0); PG8_MMA(1, 1, At, B1); PG8_BAR; PG8_SCHED;
	s_add_i32 s10, s37, s15
	v_lshl_add_u64 v[240:241], v[240:241], 0, s[62:63]
	s_mov_b32 m0, s10
	ds_read_b128 v[190:193], v208 offset:49152
	ds_read_b128 v[194:197], v208 offset:50176
	ds_read_b128 v[198:201], v208 offset:51200
	ds_read_b128 v[210:213], v208 offset:52224
	ds_read_b128 v[214:217], v208 offset:53248
	ds_read_b128 v[218:221], v208 offset:54272
	ds_read_b128 v[222:225], v208 offset:55296
	ds_read_b128 v[234:237], v208 offset:56320
	global_load_lds_dwordx4 v[240:241], off
	s_add_i32 m0, s10, 0x2000
	s_add_u32 s10, s28, 0x40080
	v_lshl_add_u64 v[240:241], v[242:243], 0, s[62:63]
	s_addc_u32 s11, s29, 0
	s_add_i32 s28, s39, s15
	global_load_lds_dwordx4 v[240:241], off
	v_lshl_add_u64 v[240:241], s[10:11], 0, v[180:181]
	s_mov_b32 m0, s28
	s_nop 0
	global_load_lds_dwordx4 v[240:241], off
	v_lshl_add_u64 v[240:241], s[10:11], 0, v[184:185]
	s_add_i32 m0, s28, 0x2000
	s_nop 0
	global_load_lds_dwordx4 v[240:241], off
	v_lshl_add_u64 v[240:241], v[244:245], 0, s[62:63]
	s_mov_b32 m0, s76
	s_nop 0
	global_load_lds_dwordx4 v[240:241], off
	v_lshl_add_u64 v[240:241], v[246:247], 0, s[62:63]
	s_mov_b32 m0, s77
	s_nop 0
	global_load_lds_dwordx4 v[240:241], off
	s_waitcnt vmcnt(8)
	s_waitcnt lgkmcnt(0)
	s_barrier
	s_setprio 1
	s_waitcnt lgkmcnt(0)
	v_mfma_f32_16x16x32_bf16 v[70:73], v[138:141], v[190:193], v[70:73]
	v_mfma_f32_16x16x32_bf16 v[66:69], v[146:149], v[190:193], v[66:69]
	v_mfma_f32_16x16x32_bf16 v[54:57], v[138:141], v[198:201], v[54:57]
	v_mfma_f32_16x16x32_bf16 v[50:53], v[146:149], v[198:201], v[50:53]
	v_mfma_f32_16x16x32_bf16 v[38:41], v[138:141], v[214:217], v[38:41]
	v_mfma_f32_16x16x32_bf16 v[34:37], v[146:149], v[214:217], v[34:37]
	v_mfma_f32_16x16x32_bf16 v[22:25], v[138:141], v[222:225], v[22:25]
	v_mfma_f32_16x16x32_bf16 v[18:21], v[146:149], v[222:225], v[18:21]
	v_mfma_f32_16x16x32_bf16 v[70:73], v[142:145], v[194:197], v[70:73]
	v_mfma_f32_16x16x32_bf16 v[66:69], v[150:153], v[194:197], v[66:69]
	v_mfma_f32_16x16x32_bf16 v[54:57], v[142:145], v[210:213], v[54:57]
	v_mfma_f32_16x16x32_bf16 v[50:53], v[150:153], v[210:213], v[50:53]
	v_mfma_f32_16x16x32_bf16 v[38:41], v[142:145], v[218:221], v[38:41]
	v_mfma_f32_16x16x32_bf16 v[34:37], v[150:153], v[218:221], v[34:37]
	v_mfma_f32_16x16x32_bf16 v[22:25], v[142:145], v[234:237], v[22:25]
	v_mfma_f32_16x16x32_bf16 v[18:21], v[150:153], v[234:237], v[18:21]
	s_setprio 0
	s_setprio 1
	v_mfma_f32_16x16x32_bf16 v[62:65], v[154:157], v[190:193], v[62:65]
	v_mfma_f32_16x16x32_bf16 v[58:61], v[162:165], v[190:193], v[58:61]
	v_mfma_f32_16x16x32_bf16 v[46:49], v[154:157], v[198:201], v[46:49]
	v_mfma_f32_16x16x32_bf16 v[42:45], v[162:165], v[198:201], v[42:45]
	v_mfma_f32_16x16x32_bf16 v[30:33], v[154:157], v[214:217], v[30:33]
	v_mfma_f32_16x16x32_bf16 v[26:29], v[162:165], v[214:217], v[26:29]
	v_mfma_f32_16x16x32_bf16 v[14:17], v[154:157], v[222:225], v[14:17]
	v_mfma_f32_16x16x32_bf16 v[10:13], v[162:165], v[222:225], v[10:13]
	v_mfma_f32_16x16x32_bf16 v[62:65], v[158:161], v[194:197], v[62:65]
	v_mfma_f32_16x16x32_bf16 v[58:61], v[166:169], v[194:197], v[58:61]
	v_mfma_f32_16x16x32_bf16 v[46:49], v[158:161], v[210:213], v[46:49]
	v_mfma_f32_16x16x32_bf16 v[42:45], v[166:169], v[210:213], v[42:45]
	v_mfma_f32_16x16x32_bf16 v[30:33], v[158:161], v[218:221], v[30:33]
	v_mfma_f32_16x16x32_bf16 v[26:29], v[166:169], v[218:221], v[26:29]
	v_mfma_f32_16x16x32_bf16 v[14:17], v[158:161], v[234:237], v[14:17]
	v_mfma_f32_16x16x32_bf16 v[10:13], v[166:169], v[234:237], v[10:13]
	s_setprio 0
	s_barrier
	s_add_i32 s5, s5, 2
	s_add_u32 s8, s8, 0x100
	s_addc_u32 s9, s9, 0
	s_add_u32 s38, s38, 0x100
	s_addc_u32 s4, s4, 0
	s_cmp_gt_u32 s5, 13
	s_cbranch_scc0 .LBB0_90
	s_and_b64 vcc, exec, s[16:17]
	s_cbranch_vccz .LBB0_93
	s_barrier

; #define PG8_LAS __attribute__((address_space(3)))
;     __device__ __forceinline__ void load(const Unit& u, int wr, int wc, int fr, int fq, const f32x4 pfa, const f32x4 pfb) {
;     ...
;         asm volatile("s_waitcnt lgkmcnt(0)" ::: "memory"); __builtin_amdgcn_s_barrier(); asm volatile("" ::: "memory");
;         const int cl = wc * 32 + 8 * fq;
; #pragma unroll
;         for (int bj = 0; bj < 2; ++bj)
; #pragma unroll
;             for (int n = 0; n < 2; ++n) { c[bj][n] = *(const PG8_LAS f32x4*)(CB + cl + bj * HALF + 4 * n); b[bj][n] = *(const PG8_LAS f32x4*)(CB + 256 + cl + bj * HALF + 4 * n); }
; #pragma unroll
;         for (int ai = 0; ai < 2; ++ai)
; #pragma unroll
;             for (int m = 0; m < 4; ++m) { const f32x2_t v = *(const PG8_LAS f32x2_t*)(T + 2 * (ai * HALF + wr * 64 + m * 16 + fr)); mu[ai][m] = v.x; rs[ai][m] = v.y; }
;     }
.LBB0_100:
	s_or_b64 exec, exec, s[8:9]
	v_lshlrev_b32_e32 v190, 3, v209
	s_waitcnt lgkmcnt(0)
	s_barrier
	v_add_u32_e32 v191, s81, v190
	ds_read_b128 v[162:165], v207
	ds_read_b128 v[154:157], v207 offset:16
	ds_read_b128 v[166:169], v206
	ds_read_b128 v[158:161], v206 offset:16
	ds_read_b128 v[146:149], v206 offset:512
	ds_read_b128 v[138:141], v206 offset:528
	ds_read_b128 v[150:153], v207 offset:512
	ds_read_b128 v[142:145], v207 offset:528
	v_add_u32_e32 v192, s82, v190
	v_add_u32_e32 v193, s83, v190
	v_add_u32_e32 v194, s86, v190
	ds_read_b64 v[210:211], v191
	ds_read_b64 v[212:213], v192
	ds_read_b64 v[200:201], v193
	ds_read_b64 v[198:199], v194
	s_waitcnt lgkmcnt(0)
	v_xor_b32_e32 v169, 0x80000000, v169
	v_pk_fma_f32 v[134:135], v[166:167], v[210:211], v[134:135] op_sel_hi:[1,0,1] neg_lo:[1,0,0] neg_hi:[1,0,0]
	v_xor_b32_e32 v168, 0x80000000, v168
	v_pk_fma_f32 v[216:217], v[210:211], v[134:135], v[162:163] op_sel:[1,0,0]
	v_xor_b32_e32 v135, 0x80000000, v161
	v_xor_b32_e32 v134, 0x80000000, v160
	s_lshl_b32 s4, s26, 8
	v_pk_fma_f32 v[136:137], v[168:169], v[210:211], v[136:137] op_sel_hi:[1,0,1]
	v_pk_fma_f32 v[132:133], v[134:135], v[210:211], v[132:133] op_sel_hi:[1,0,1]
	v_pk_fma_f32 v[130:131], v[158:159], v[210:211], v[130:131] op_sel_hi:[1,0,1] neg_lo:[1,0,0] neg_hi:[1,0,0]
	s_add_i32 s4, s4, s50
	v_pk_fma_f32 v[136:137], v[210:211], v[136:137], v[164:165] op_sel:[1,0,0]
	v_pk_fma_f32 v[132:133], v[210:211], v[132:133], v[156:157] op_sel:[1,0,0]
	v_pk_fma_f32 v[130:131], v[210:211], v[130:131], v[154:155] op_sel:[1,0,0]
	v_or_b32_e32 v0, v0, v204
	v_add_u32_e32 v209, s4, v209
	v_max_f32_e32 v161, 0, v217
	v_max_f32_e32 v160, 0, v216
	v_max_f32_e32 v137, 0, v137
	v_max_f32_e32 v136, 0, v136
	v_max_f32_e32 v131, 0, v131
	v_max_f32_e32 v130, 0, v130
	v_max_f32_e32 v133, 0, v133
	v_max_f32_e32 v132, 0, v132
	v_lshl_add_u32 v0, v209, 12, v0
	v_pk_mul_f32 v[136:137], v[136:137], v[136:137]
	v_pk_mul_f32 v[160:161], v[160:161], v[160:161]
	v_pk_mul_f32 v[216:217], v[132:133], v[132:133]
	v_pk_mul_f32 v[132:133], v[130:131], v[130:131]
	v_add_u32_e32 v191, s87, v190
	v_add_u32_e32 v192, s91, v190
	v_add_u32_e32 v193, s0, v190
	v_add_u32_e32 v190, s1, v190
	v_lshl_add_u64 v[214:215], v[0:1], 1, s[74:75]
	v_cvt_pk_bf16_f32 v130, v160, v161
	v_cvt_pk_bf16_f32 v131, v136, v137
	v_cvt_pk_bf16_f32 v132, v132, v133
	v_cvt_pk_bf16_f32 v133, v216, v217
	v_pk_fma_f32 v[126:127], v[146:147], v[210:211], v[126:127] op_sel_hi:[1,0,1] neg_lo:[1,0,0] neg_hi:[1,0,0]
	ds_read_b64 v[196:197], v191
	ds_read_b64 v[194:195], v192
	ds_read_b64 v[192:193], v193
	ds_read_b64 v[190:191], v190
	global_store_dwordx4 v[214:215], v[130:133], off
	v_pk_fma_f32 v[122:123], v[138:139], v[210:211], v[122:123] op_sel_hi:[1,0,1] neg_lo:[1,0,0] neg_hi:[1,0,0]
	v_pk_fma_f32 v[120:121], v[168:169], v[212:213], v[120:121] op_sel_hi:[1,0,1]
	v_xor_b32_e32 v131, 0x80000000, v149
	v_xor_b32_e32 v130, 0x80000000, v148
	v_pk_fma_f32 v[132:133], v[210:211], v[126:127], v[150:151] op_sel:[1,0,0]
	v_xor_b32_e32 v127, 0x80000000, v141
	v_xor_b32_e32 v126, 0x80000000, v140
	v_pk_fma_f32 v[128:129], v[130:131], v[210:211], v[128:129] op_sel_hi:[1,0,1]
	v_pk_fma_f32 v[124:125], v[126:127], v[210:211], v[124:125] op_sel_hi:[1,0,1]
	v_pk_fma_f32 v[128:129], v[210:211], v[128:129], v[152:153] op_sel:[1,0,0]
	v_pk_fma_f32 v[124:125], v[210:211], v[124:125], v[144:145] op_sel:[1,0,0]
	v_pk_fma_f32 v[122:123], v[210:211], v[122:123], v[142:143] op_sel:[1,0,0]
	v_max_f32_e32 v133, 0, v133
	v_max_f32_e32 v132, 0, v132
	v_max_f32_e32 v129, 0, v129
	v_max_f32_e32 v128, 0, v128
	v_max_f32_e32 v123, 0, v123
	v_max_f32_e32 v122, 0, v122
	v_max_f32_e32 v125, 0, v125
	v_max_f32_e32 v124, 0, v124
	v_pk_fma_f32 v[118:119], v[166:167], v[212:213], v[118:119] op_sel_hi:[1,0,1] neg_lo:[1,0,0] neg_hi:[1,0,0]
	v_pk_fma_f32 v[116:117], v[134:135], v[212:213], v[116:117] op_sel_hi:[1,0,1]
	v_pk_fma_f32 v[114:115], v[158:159], v[212:213], v[114:115] op_sel_hi:[1,0,1] neg_lo:[1,0,0] neg_hi:[1,0,0]
	v_pk_mul_f32 v[128:129], v[128:129], v[128:129]
	v_pk_mul_f32 v[132:133], v[132:133], v[132:133]
	v_pk_mul_f32 v[136:137], v[124:125], v[124:125]
	v_pk_mul_f32 v[124:125], v[122:123], v[122:123]
	v_pk_fma_f32 v[120:121], v[212:213], v[120:121], v[164:165] op_sel:[1,0,0]
	v_pk_fma_f32 v[118:119], v[212:213], v[118:119], v[162:163] op_sel:[1,0,0]
	v_pk_fma_f32 v[116:117], v[212:213], v[116:117], v[156:157] op_sel:[1,0,0]
	v_pk_fma_f32 v[114:115], v[212:213], v[114:115], v[154:155] op_sel:[1,0,0]
	v_cvt_pk_bf16_f32 v122, v132, v133
	v_cvt_pk_bf16_f32 v123, v128, v129
	v_cvt_pk_bf16_f32 v124, v124, v125
	v_cvt_pk_bf16_f32 v125, v136, v137
	v_max_f32_e32 v119, 0, v119
	v_max_f32_e32 v118, 0, v118
	v_max_f32_e32 v121, 0, v121
	v_max_f32_e32 v120, 0, v120
	v_max_f32_e32 v115, 0, v115
	v_max_f32_e32 v114, 0, v114
	v_max_f32_e32 v117, 0, v117
	v_max_f32_e32 v116, 0, v116
	v_pk_fma_f32 v[112:113], v[130:131], v[212:213], v[112:113] op_sel_hi:[1,0,1]
	v_pk_fma_f32 v[110:111], v[146:147], v[212:213], v[110:111] op_sel_hi:[1,0,1] neg_lo:[1,0,0] neg_hi:[1,0,0]
	v_pk_fma_f32 v[108:109], v[126:127], v[212:213], v[108:109] op_sel_hi:[1,0,1]
	v_pk_fma_f32 v[106:107], v[138:139], v[212:213], v[106:107] op_sel_hi:[1,0,1] neg_lo:[1,0,0] neg_hi:[1,0,0]
	global_store_dwordx4 v[214:215], v[122:125], off offset:256
	v_pk_mul_f32 v[120:121], v[120:121], v[120:121]
	v_pk_mul_f32 v[118:119], v[118:119], v[118:119]
	v_add_u32_e32 v122, 0x10000, v0
	v_mov_b32_e32 v123, v1
	v_pk_mul_f32 v[124:125], v[116:117], v[116:117]
	v_pk_mul_f32 v[116:117], v[114:115], v[114:115]
	v_pk_fma_f32 v[112:113], v[212:213], v[112:113], v[152:153] op_sel:[1,0,0]
	v_pk_fma_f32 v[110:111], v[212:213], v[110:111], v[150:151] op_sel:[1,0,0]
	v_pk_fma_f32 v[108:109], v[212:213], v[108:109], v[144:145] op_sel:[1,0,0]
	v_pk_fma_f32 v[106:107], v[212:213], v[106:107], v[142:143] op_sel:[1,0,0]
	v_lshl_add_u64 v[122:123], v[122:123], 1, s[74:75]
	v_cvt_pk_bf16_f32 v114, v118, v119
	v_cvt_pk_bf16_f32 v115, v120, v121
	v_cvt_pk_bf16_f32 v116, v116, v117
	v_cvt_pk_bf16_f32 v117, v124, v125
	v_max_f32_e32 v111, 0, v111
	v_max_f32_e32 v110, 0, v110
	v_max_f32_e32 v113, 0, v113
	v_max_f32_e32 v112, 0, v112
	v_max_f32_e32 v107, 0, v107
	v_max_f32_e32 v106, 0, v106
	v_max_f32_e32 v109, 0, v109
	v_max_f32_e32 v108, 0, v108
	v_pk_fma_f32 v[104:105], v[168:169], v[200:201], v[104:105] op_sel_hi:[1,0,1]
	v_pk_fma_f32 v[102:103], v[166:167], v[200:201], v[102:103] op_sel_hi:[1,0,1] neg_lo:[1,0,0] neg_hi:[1,0,0]
	v_pk_fma_f32 v[100:101], v[134:135], v[200:201], v[100:101] op_sel_hi:[1,0,1]
	v_pk_fma_f32 v[98:99], v[158:159], v[200:201], v[98:99] op_sel_hi:[1,0,1] neg_lo:[1,0,0] neg_hi:[1,0,0]
	global_store_dwordx4 v[122:123], v[114:117], off
	v_pk_mul_f32 v[112:113], v[112:113], v[112:113]
	v_pk_mul_f32 v[110:111], v[110:111], v[110:111]
	v_pk_mul_f32 v[114:115], v[108:109], v[108:109]
	v_pk_mul_f32 v[108:109], v[106:107], v[106:107]
	v_pk_fma_f32 v[104:105], v[200:201], v[104:105], v[164:165] op_sel:[1,0,0]
	v_pk_fma_f32 v[102:103], v[200:201], v[102:103], v[162:163] op_sel:[1,0,0]
	v_pk_fma_f32 v[100:101], v[200:201], v[100:101], v[156:157] op_sel:[1,0,0]
	v_pk_fma_f32 v[98:99], v[200:201], v[98:99], v[154:155] op_sel:[1,0,0]
	v_cvt_pk_bf16_f32 v106, v110, v111
	v_cvt_pk_bf16_f32 v107, v112, v113
	v_cvt_pk_bf16_f32 v108, v108, v109
	v_cvt_pk_bf16_f32 v109, v114, v115
	v_max_f32_e32 v103, 0, v103
	v_max_f32_e32 v102, 0, v102
	v_max_f32_e32 v105, 0, v105
	v_max_f32_e32 v104, 0, v104
	v_max_f32_e32 v99, 0, v99
	v_max_f32_e32 v98, 0, v98
	v_max_f32_e32 v101, 0, v101
	v_max_f32_e32 v100, 0, v100
	v_pk_fma_f32 v[96:97], v[130:131], v[200:201], v[96:97] op_sel_hi:[1,0,1]
	v_pk_fma_f32 v[94:95], v[146:147], v[200:201], v[94:95] op_sel_hi:[1,0,1] neg_lo:[1,0,0] neg_hi:[1,0,0]
	v_pk_fma_f32 v[92:93], v[126:127], v[200:201], v[92:93] op_sel_hi:[1,0,1]
	v_pk_fma_f32 v[90:91], v[138:139], v[200:201], v[90:91] op_sel_hi:[1,0,1] neg_lo:[1,0,0] neg_hi:[1,0,0]
	global_store_dwordx4 v[122:123], v[106:109], off offset:256
	v_pk_mul_f32 v[104:105], v[104:105], v[104:105]
	v_pk_mul_f32 v[102:103], v[102:103], v[102:103]
	v_add_u32_e32 v106, 0x20000, v0
	v_mov_b32_e32 v107, v1
	v_pk_mul_f32 v[108:109], v[100:101], v[100:101]
	v_pk_mul_f32 v[100:101], v[98:99], v[98:99]
	v_pk_fma_f32 v[96:97], v[200:201], v[96:97], v[152:153] op_sel:[1,0,0]
	v_pk_fma_f32 v[94:95], v[200:201], v[94:95], v[150:151] op_sel:[1,0,0]
	v_pk_fma_f32 v[92:93], v[200:201], v[92:93], v[144:145] op_sel:[1,0,0]
	v_pk_fma_f32 v[90:91], v[200:201], v[90:91], v[142:143] op_sel:[1,0,0]
	v_lshl_add_u64 v[106:107], v[106:107], 1, s[74:75]
	v_cvt_pk_bf16_f32 v98, v102, v103
	v_cvt_pk_bf16_f32 v99, v104, v105
	v_cvt_pk_bf16_f32 v100, v100, v101
	v_cvt_pk_bf16_f32 v101, v108, v109
	v_max_f32_e32 v95, 0, v95
	v_max_f32_e32 v94, 0, v94
	v_max_f32_e32 v97, 0, v97
	v_max_f32_e32 v96, 0, v96
	v_max_f32_e32 v91, 0, v91
	v_max_f32_e32 v90, 0, v90
	v_max_f32_e32 v93, 0, v93
	v_max_f32_e32 v92, 0, v92
	v_pk_fma_f32 v[88:89], v[168:169], v[198:199], v[88:89] op_sel_hi:[1,0,1]
	v_pk_fma_f32 v[86:87], v[166:167], v[198:199], v[86:87] op_sel_hi:[1,0,1] neg_lo:[1,0,0] neg_hi:[1,0,0]
	v_pk_fma_f32 v[84:85], v[134:135], v[198:199], v[84:85] op_sel_hi:[1,0,1]
	v_pk_fma_f32 v[82:83], v[158:159], v[198:199], v[82:83] op_sel_hi:[1,0,1] neg_lo:[1,0,0] neg_hi:[1,0,0]
	global_store_dwordx4 v[106:107], v[98:101], off
	v_pk_mul_f32 v[96:97], v[96:97], v[96:97]
	v_pk_mul_f32 v[94:95], v[94:95], v[94:95]
	v_pk_mul_f32 v[98:99], v[92:93], v[92:93]
	v_pk_mul_f32 v[92:93], v[90:91], v[90:91]
	v_pk_fma_f32 v[88:89], v[198:199], v[88:89], v[164:165] op_sel:[1,0,0]
	v_pk_fma_f32 v[86:87], v[198:199], v[86:87], v[162:163] op_sel:[1,0,0]
	v_pk_fma_f32 v[84:85], v[198:199], v[84:85], v[156:157] op_sel:[1,0,0]
	v_pk_fma_f32 v[82:83], v[198:199], v[82:83], v[154:155] op_sel:[1,0,0]
	v_cvt_pk_bf16_f32 v90, v94, v95
	v_cvt_pk_bf16_f32 v91, v96, v97
	v_cvt_pk_bf16_f32 v92, v92, v93
	v_cvt_pk_bf16_f32 v93, v98, v99
	v_max_f32_e32 v87, 0, v87
	v_max_f32_e32 v86, 0, v86
	v_max_f32_e32 v89, 0, v89
	v_max_f32_e32 v88, 0, v88
	v_max_f32_e32 v83, 0, v83
	v_max_f32_e32 v82, 0, v82
	v_max_f32_e32 v85, 0, v85
	v_max_f32_e32 v84, 0, v84
	v_pk_fma_f32 v[80:81], v[130:131], v[198:199], v[80:81] op_sel_hi:[1,0,1]
	v_pk_fma_f32 v[78:79], v[146:147], v[198:199], v[78:79] op_sel_hi:[1,0,1] neg_lo:[1,0,0] neg_hi:[1,0,0]
	v_pk_fma_f32 v[76:77], v[126:127], v[198:199], v[76:77] op_sel_hi:[1,0,1]
	v_pk_fma_f32 v[74:75], v[138:139], v[198:199], v[74:75] op_sel_hi:[1,0,1] neg_lo:[1,0,0] neg_hi:[1,0,0]
	global_store_dwordx4 v[106:107], v[90:93], off offset:256
	v_pk_mul_f32 v[88:89], v[88:89], v[88:89]
	v_pk_mul_f32 v[86:87], v[86:87], v[86:87]
	v_add_u32_e32 v90, 0x30000, v0
	v_mov_b32_e32 v91, v1
	v_pk_mul_f32 v[92:93], v[84:85], v[84:85]
	v_pk_mul_f32 v[84:85], v[82:83], v[82:83]
	v_pk_fma_f32 v[80:81], v[198:199], v[80:81], v[152:153] op_sel:[1,0,0]
	v_pk_fma_f32 v[78:79], v[198:199], v[78:79], v[150:151] op_sel:[1,0,0]
	v_pk_fma_f32 v[76:77], v[198:199], v[76:77], v[144:145] op_sel:[1,0,0]
	v_pk_fma_f32 v[74:75], v[198:199], v[74:75], v[142:143] op_sel:[1,0,0]
	v_lshl_add_u64 v[90:91], v[90:91], 1, s[74:75]
	v_cvt_pk_bf16_f32 v82, v86, v87
	v_cvt_pk_bf16_f32 v83, v88, v89
	v_cvt_pk_bf16_f32 v84, v84, v85
	v_cvt_pk_bf16_f32 v85, v92, v93
	v_max_f32_e32 v79, 0, v79
	v_max_f32_e32 v78, 0, v78
	v_max_f32_e32 v81, 0, v81
	v_max_f32_e32 v80, 0, v80
	v_max_f32_e32 v75, 0, v75
	v_max_f32_e32 v74, 0, v74
	v_max_f32_e32 v77, 0, v77
	v_max_f32_e32 v76, 0, v76
	s_waitcnt lgkmcnt(0)
	v_pk_fma_f32 v[72:73], v[168:169], v[196:197], v[72:73] op_sel_hi:[1,0,1]
	v_pk_fma_f32 v[70:71], v[166:167], v[196:197], v[70:71] op_sel_hi:[1,0,1] neg_lo:[1,0,0] neg_hi:[1,0,0]
	v_pk_fma_f32 v[68:69], v[134:135], v[196:197], v[68:69] op_sel_hi:[1,0,1]
	v_pk_fma_f32 v[66:67], v[158:159], v[196:197], v[66:67] op_sel_hi:[1,0,1] neg_lo:[1,0,0] neg_hi:[1,0,0]
	global_store_dwordx4 v[90:91], v[82:85], off
	v_pk_mul_f32 v[80:81], v[80:81], v[80:81]
	v_pk_mul_f32 v[78:79], v[78:79], v[78:79]
	v_pk_mul_f32 v[82:83], v[76:77], v[76:77]
	v_pk_mul_f32 v[76:77], v[74:75], v[74:75]
	v_pk_fma_f32 v[72:73], v[196:197], v[72:73], v[164:165] op_sel:[1,0,0]
	v_pk_fma_f32 v[70:71], v[196:197], v[70:71], v[162:163] op_sel:[1,0,0]
	v_pk_fma_f32 v[68:69], v[196:197], v[68:69], v[156:157] op_sel:[1,0,0]
	v_pk_fma_f32 v[66:67], v[196:197], v[66:67], v[154:155] op_sel:[1,0,0]
	v_cvt_pk_bf16_f32 v74, v78, v79
	v_cvt_pk_bf16_f32 v75, v80, v81
	v_cvt_pk_bf16_f32 v76, v76, v77
	v_cvt_pk_bf16_f32 v77, v82, v83
	v_max_f32_e32 v71, 0, v71
	v_max_f32_e32 v70, 0, v70
	v_max_f32_e32 v73, 0, v73
	v_max_f32_e32 v72, 0, v72
	v_max_f32_e32 v67, 0, v67
	v_max_f32_e32 v66, 0, v66
	v_max_f32_e32 v69, 0, v69
	v_max_f32_e32 v68, 0, v68
	v_pk_fma_f32 v[64:65], v[130:131], v[196:197], v[64:65] op_sel_hi:[1,0,1]
	v_pk_fma_f32 v[62:63], v[146:147], v[196:197], v[62:63] op_sel_hi:[1,0,1] neg_lo:[1,0,0] neg_hi:[1,0,0]
	v_pk_fma_f32 v[60:61], v[126:127], v[196:197], v[60:61] op_sel_hi:[1,0,1]
	v_pk_fma_f32 v[58:59], v[138:139], v[196:197], v[58:59] op_sel_hi:[1,0,1] neg_lo:[1,0,0] neg_hi:[1,0,0]
	global_store_dwordx4 v[90:91], v[74:77], off offset:256
	v_pk_mul_f32 v[72:73], v[72:73], v[72:73]
	v_pk_mul_f32 v[70:71], v[70:71], v[70:71]
	v_add_u32_e32 v74, 0x80000, v0
	v_mov_b32_e32 v75, v1
	v_pk_mul_f32 v[76:77], v[68:69], v[68:69]
	v_pk_mul_f32 v[68:69], v[66:67], v[66:67]
	v_pk_fma_f32 v[64:65], v[196:197], v[64:65], v[152:153] op_sel:[1,0,0]
	v_pk_fma_f32 v[62:63], v[196:197], v[62:63], v[150:151] op_sel:[1,0,0]
	v_pk_fma_f32 v[60:61], v[196:197], v[60:61], v[144:145] op_sel:[1,0,0]
	v_pk_fma_f32 v[58:59], v[196:197], v[58:59], v[142:143] op_sel:[1,0,0]
	v_lshl_add_u64 v[74:75], v[74:75], 1, s[74:75]
	v_cvt_pk_bf16_f32 v66, v70, v71
	v_cvt_pk_bf16_f32 v67, v72, v73
	v_cvt_pk_bf16_f32 v68, v68, v69
	v_cvt_pk_bf16_f32 v69, v76, v77
	v_max_f32_e32 v63, 0, v63
	v_max_f32_e32 v62, 0, v62
	v_max_f32_e32 v65, 0, v65
	v_max_f32_e32 v64, 0, v64
	v_max_f32_e32 v59, 0, v59
	v_max_f32_e32 v58, 0, v58
	v_max_f32_e32 v61, 0, v61
	v_max_f32_e32 v60, 0, v60
	v_pk_fma_f32 v[56:57], v[168:169], v[194:195], v[56:57] op_sel_hi:[1,0,1]
	v_pk_fma_f32 v[54:55], v[166:167], v[194:195], v[54:55] op_sel_hi:[1,0,1] neg_lo:[1,0,0] neg_hi:[1,0,0]
	v_pk_fma_f32 v[52:53], v[134:135], v[194:195], v[52:53] op_sel_hi:[1,0,1]
	v_pk_fma_f32 v[50:51], v[158:159], v[194:195], v[50:51] op_sel_hi:[1,0,1] neg_lo:[1,0,0] neg_hi:[1,0,0]
	global_store_dwordx4 v[74:75], v[66:69], off
	v_pk_mul_f32 v[64:65], v[64:65], v[64:65]
	v_pk_mul_f32 v[62:63], v[62:63], v[62:63]
	v_pk_mul_f32 v[66:67], v[60:61], v[60:61]
	v_pk_mul_f32 v[60:61], v[58:59], v[58:59]
	v_pk_fma_f32 v[56:57], v[194:195], v[56:57], v[164:165] op_sel:[1,0,0]
	v_pk_fma_f32 v[54:55], v[194:195], v[54:55], v[162:163] op_sel:[1,0,0]
	v_pk_fma_f32 v[52:53], v[194:195], v[52:53], v[156:157] op_sel:[1,0,0]
	v_pk_fma_f32 v[50:51], v[194:195], v[50:51], v[154:155] op_sel:[1,0,0]
	v_cvt_pk_bf16_f32 v58, v62, v63
	v_cvt_pk_bf16_f32 v59, v64, v65
	v_cvt_pk_bf16_f32 v60, v60, v61
	v_cvt_pk_bf16_f32 v61, v66, v67
	v_max_f32_e32 v55, 0, v55
	v_max_f32_e32 v54, 0, v54
	v_max_f32_e32 v57, 0, v57
	v_max_f32_e32 v56, 0, v56
	v_max_f32_e32 v51, 0, v51
	v_max_f32_e32 v50, 0, v50
	v_max_f32_e32 v53, 0, v53
	v_max_f32_e32 v52, 0, v52
	v_pk_fma_f32 v[48:49], v[130:131], v[194:195], v[48:49] op_sel_hi:[1,0,1]
	v_pk_fma_f32 v[46:47], v[146:147], v[194:195], v[46:47] op_sel_hi:[1,0,1] neg_lo:[1,0,0] neg_hi:[1,0,0]
	v_pk_fma_f32 v[44:45], v[126:127], v[194:195], v[44:45] op_sel_hi:[1,0,1]
	v_pk_fma_f32 v[42:43], v[138:139], v[194:195], v[42:43] op_sel_hi:[1,0,1] neg_lo:[1,0,0] neg_hi:[1,0,0]
	global_store_dwordx4 v[74:75], v[58:61], off offset:256
	v_pk_mul_f32 v[56:57], v[56:57], v[56:57]
	v_pk_mul_f32 v[54:55], v[54:55], v[54:55]
	v_add_u32_e32 v58, 0x90000, v0
	v_mov_b32_e32 v59, v1
	v_pk_mul_f32 v[60:61], v[52:53], v[52:53]
	v_pk_mul_f32 v[52:53], v[50:51], v[50:51]
	v_pk_fma_f32 v[48:49], v[194:195], v[48:49], v[152:153] op_sel:[1,0,0]
	v_pk_fma_f32 v[46:47], v[194:195], v[46:47], v[150:151] op_sel:[1,0,0]
	v_pk_fma_f32 v[44:45], v[194:195], v[44:45], v[144:145] op_sel:[1,0,0]
	v_pk_fma_f32 v[42:43], v[194:195], v[42:43], v[142:143] op_sel:[1,0,0]
	v_lshl_add_u64 v[58:59], v[58:59], 1, s[74:75]
	v_cvt_pk_bf16_f32 v50, v54, v55
	v_cvt_pk_bf16_f32 v51, v56, v57
	v_cvt_pk_bf16_f32 v52, v52, v53
	v_cvt_pk_bf16_f32 v53, v60, v61
	v_max_f32_e32 v47, 0, v47
	v_max_f32_e32 v46, 0, v46
	v_max_f32_e32 v49, 0, v49
	v_max_f32_e32 v48, 0, v48
	v_max_f32_e32 v43, 0, v43
	v_max_f32_e32 v42, 0, v42
	v_max_f32_e32 v45, 0, v45
	v_max_f32_e32 v44, 0, v44
	v_pk_fma_f32 v[40:41], v[168:169], v[192:193], v[40:41] op_sel_hi:[1,0,1]
	v_pk_fma_f32 v[38:39], v[166:167], v[192:193], v[38:39] op_sel_hi:[1,0,1] neg_lo:[1,0,0] neg_hi:[1,0,0]
	v_pk_fma_f32 v[36:37], v[134:135], v[192:193], v[36:37] op_sel_hi:[1,0,1]
	v_pk_fma_f32 v[34:35], v[158:159], v[192:193], v[34:35] op_sel_hi:[1,0,1] neg_lo:[1,0,0] neg_hi:[1,0,0]
	global_store_dwordx4 v[58:59], v[50:53], off
	v_pk_mul_f32 v[48:49], v[48:49], v[48:49]
; template <class Epi, class Sched, bool ALIGN_EPI = false, bool SP2 = false>
; __device__ __forceinline__ void gemm_phase(PG8_LAS unsigned char* lds, const Gemm g, const Sched& S, const Epi& E, const int wave_id) {
;     ...
;         if (!has_next) break;
; #pragma unroll
;         for (int a = 0; a < 2; ++a)
; #pragma unroll
;             for (int b = 0; b < 2; ++b)
; #pragma unroll
;                 for (int m = 0; m < 4; ++m)
; #pragma unroll
;                     for (int n = 0; n < 2; ++n) acc[a][b][m][n] = (f32x4){0.f, 0.f, 0.f, 0.f};
;         cur = nxt; cA = nA; cB = nB; ++ui;
;         if constexpr (Epi::HAS_PF) E.prefetch(cur, tid);
	v_pk_mul_f32 v[46:47], v[46:47], v[46:47]
	v_pk_mul_f32 v[50:51], v[44:45], v[44:45]
	v_pk_mul_f32 v[44:45], v[42:43], v[42:43]
	v_pk_fma_f32 v[40:41], v[192:193], v[40:41], v[164:165] op_sel:[1,0,0]
	v_pk_fma_f32 v[38:39], v[192:193], v[38:39], v[162:163] op_sel:[1,0,0]
	v_pk_fma_f32 v[36:37], v[192:193], v[36:37], v[156:157] op_sel:[1,0,0]
	v_pk_fma_f32 v[34:35], v[192:193], v[34:35], v[154:155] op_sel:[1,0,0]
	v_cvt_pk_bf16_f32 v42, v46, v47
	v_cvt_pk_bf16_f32 v43, v48, v49
	v_cvt_pk_bf16_f32 v44, v44, v45
	v_cvt_pk_bf16_f32 v45, v50, v51
	v_max_f32_e32 v39, 0, v39
	v_max_f32_e32 v38, 0, v38
	v_max_f32_e32 v41, 0, v41
	v_max_f32_e32 v40, 0, v40
	v_max_f32_e32 v35, 0, v35
	v_max_f32_e32 v34, 0, v34
	v_max_f32_e32 v37, 0, v37
	v_max_f32_e32 v36, 0, v36
	v_pk_fma_f32 v[32:33], v[130:131], v[192:193], v[32:33] op_sel_hi:[1,0,1]
	v_pk_fma_f32 v[30:31], v[146:147], v[192:193], v[30:31] op_sel_hi:[1,0,1] neg_lo:[1,0,0] neg_hi:[1,0,0]
	v_pk_fma_f32 v[28:29], v[126:127], v[192:193], v[28:29] op_sel_hi:[1,0,1]
	v_pk_fma_f32 v[26:27], v[138:139], v[192:193], v[26:27] op_sel_hi:[1,0,1] neg_lo:[1,0,0] neg_hi:[1,0,0]
	global_store_dwordx4 v[58:59], v[42:45], off offset:256
	v_pk_mul_f32 v[40:41], v[40:41], v[40:41]
	v_pk_mul_f32 v[38:39], v[38:39], v[38:39]
	v_add_u32_e32 v42, 0xa0000, v0
	v_mov_b32_e32 v43, v1
	v_pk_mul_f32 v[44:45], v[36:37], v[36:37]
	v_pk_mul_f32 v[36:37], v[34:35], v[34:35]
	v_pk_fma_f32 v[32:33], v[192:193], v[32:33], v[152:153] op_sel:[1,0,0]
	v_pk_fma_f32 v[30:31], v[192:193], v[30:31], v[150:151] op_sel:[1,0,0]
	v_pk_fma_f32 v[28:29], v[192:193], v[28:29], v[144:145] op_sel:[1,0,0]
	v_pk_fma_f32 v[26:27], v[192:193], v[26:27], v[142:143] op_sel:[1,0,0]
	v_lshl_add_u64 v[42:43], v[42:43], 1, s[74:75]
	v_cvt_pk_bf16_f32 v34, v38, v39
	v_cvt_pk_bf16_f32 v35, v40, v41
	v_cvt_pk_bf16_f32 v36, v36, v37
	v_cvt_pk_bf16_f32 v37, v44, v45
	v_max_f32_e32 v31, 0, v31
	v_max_f32_e32 v30, 0, v30
	v_max_f32_e32 v33, 0, v33
	v_max_f32_e32 v32, 0, v32
	v_max_f32_e32 v27, 0, v27
	v_max_f32_e32 v26, 0, v26
	v_max_f32_e32 v29, 0, v29
	v_max_f32_e32 v28, 0, v28
	v_pk_fma_f32 v[24:25], v[168:169], v[190:191], v[24:25] op_sel_hi:[1,0,1]
	v_pk_fma_f32 v[22:23], v[166:167], v[190:191], v[22:23] op_sel_hi:[1,0,1] neg_lo:[1,0,0] neg_hi:[1,0,0]
	v_pk_fma_f32 v[20:21], v[134:135], v[190:191], v[20:21] op_sel_hi:[1,0,1]
	v_pk_fma_f32 v[18:19], v[158:159], v[190:191], v[18:19] op_sel_hi:[1,0,1] neg_lo:[1,0,0] neg_hi:[1,0,0]
	global_store_dwordx4 v[42:43], v[34:37], off
	v_pk_mul_f32 v[32:33], v[32:33], v[32:33]
	v_pk_mul_f32 v[30:31], v[30:31], v[30:31]
	v_pk_mul_f32 v[34:35], v[28:29], v[28:29]
	v_pk_mul_f32 v[28:29], v[26:27], v[26:27]
	v_pk_fma_f32 v[24:25], v[190:191], v[24:25], v[164:165] op_sel:[1,0,0]
	v_pk_fma_f32 v[22:23], v[190:191], v[22:23], v[162:163] op_sel:[1,0,0]
	v_pk_fma_f32 v[20:21], v[190:191], v[20:21], v[156:157] op_sel:[1,0,0]
	v_pk_fma_f32 v[18:19], v[190:191], v[18:19], v[154:155] op_sel:[1,0,0]
	v_cvt_pk_bf16_f32 v26, v30, v31
	v_cvt_pk_bf16_f32 v27, v32, v33
	v_cvt_pk_bf16_f32 v28, v28, v29
	v_cvt_pk_bf16_f32 v29, v34, v35
	v_max_f32_e32 v23, 0, v23
	v_max_f32_e32 v22, 0, v22
	v_max_f32_e32 v25, 0, v25
	v_max_f32_e32 v24, 0, v24
	v_max_f32_e32 v19, 0, v19
	v_max_f32_e32 v18, 0, v18
	v_max_f32_e32 v21, 0, v21
	v_max_f32_e32 v20, 0, v20
	v_pk_fma_f32 v[16:17], v[130:131], v[190:191], v[16:17] op_sel_hi:[1,0,1]
	v_pk_fma_f32 v[14:15], v[146:147], v[190:191], v[14:15] op_sel_hi:[1,0,1] neg_lo:[1,0,0] neg_hi:[1,0,0]
	v_pk_fma_f32 v[12:13], v[126:127], v[190:191], v[12:13] op_sel_hi:[1,0,1]
	v_pk_fma_f32 v[10:11], v[138:139], v[190:191], v[10:11] op_sel_hi:[1,0,1] neg_lo:[1,0,0] neg_hi:[1,0,0]
	global_store_dwordx4 v[42:43], v[26:29], off offset:256
	v_add_u32_e32 v0, 0xb0000, v0
	v_pk_mul_f32 v[24:25], v[24:25], v[24:25]
	v_pk_mul_f32 v[22:23], v[22:23], v[22:23]
	v_pk_mul_f32 v[28:29], v[20:21], v[20:21]
	v_pk_mul_f32 v[20:21], v[18:19], v[18:19]
	v_pk_fma_f32 v[16:17], v[190:191], v[16:17], v[152:153] op_sel:[1,0,0]
	v_pk_fma_f32 v[14:15], v[190:191], v[14:15], v[150:151] op_sel:[1,0,0]
	v_pk_fma_f32 v[12:13], v[190:191], v[12:13], v[144:145] op_sel:[1,0,0]
	v_pk_fma_f32 v[10:11], v[190:191], v[10:11], v[142:143] op_sel:[1,0,0]
	v_lshl_add_u64 v[26:27], v[0:1], 1, s[74:75]
	v_cvt_pk_bf16_f32 v18, v22, v23
	v_cvt_pk_bf16_f32 v19, v24, v25
	v_cvt_pk_bf16_f32 v20, v20, v21
	v_cvt_pk_bf16_f32 v21, v28, v29
	v_max_f32_e32 v15, 0, v15
	v_max_f32_e32 v14, 0, v14
	v_max_f32_e32 v17, 0, v17
	v_max_f32_e32 v16, 0, v16
	v_max_f32_e32 v11, 0, v11
	v_max_f32_e32 v10, 0, v10
	v_max_f32_e32 v13, 0, v13
	v_max_f32_e32 v12, 0, v12
	global_store_dwordx4 v[26:27], v[18:21], off
	v_pk_mul_f32 v[16:17], v[16:17], v[16:17]
	v_pk_mul_f32 v[14:15], v[14:15], v[14:15]
	v_pk_mul_f32 v[18:19], v[12:13], v[12:13]
	v_pk_mul_f32 v[12:13], v[10:11], v[10:11]
	v_cvt_pk_bf16_f32 v10, v14, v15
	v_cvt_pk_bf16_f32 v11, v16, v17
	v_cvt_pk_bf16_f32 v12, v12, v13
	v_cvt_pk_bf16_f32 v13, v18, v19
	s_andn2_b64 vcc, exec, s[6:7]
	s_mov_b64 s[6:7], -1
	global_store_dwordx4 v[26:27], v[10:13], off offset:256
	s_cbranch_vccnz .LBB0_86
	s_mov_b32 s98, 1
	s_mov_b64 s[6:7], exec
	v_readlane_b32 s4, v255, 0
	v_readlane_b32 s5, v255, 1
	s_and_b64 s[4:5], s[6:7], s[4:5]
	s_mov_b64 exec, s[4:5]
	s_cbranch_execz .LBB0_103
	v_readlane_b32 s4, v254, 60
	v_lshl_add_u32 v0, s20, 11, v175
	v_readlane_b32 s5, v254, 61
	s_nop 0
	v_lshl_add_u64 v[6:7], v[0:1], 2, s[4:5]
	global_load_dwordx4 v[2:5], v[6:7], off offset:16
	s_nop 0
	global_load_dwordx4 v[6:9], v[6:7], off

; #define PG8_STAGE(bufoff, gbase, voff) do { _Pragma("unroll") for (int _i = 0; _i < 2; ++_i) \
;         __builtin_amdgcn_global_load_lds((const unsigned*)((const char*)(gbase) + (voff)[_i]), (PG8_LAS unsigned*)(lds + (bufoff) + ldsw + _i * 8192), 16, 0, 0); } while (0)
; #define PG8_LDA(dst, b, h) do { _Pragma("unroll") for (int m = 0; m < 4; ++m) _Pragma("unroll") for (int k = 0; k < 2; ++k) dst[m][k] = *(const PG8_LAS bf16x8*)(lds + PG8_SA(b, h) + aoff + m * 2048 + k * 1024); } while (0)
; #define PG8_LDB(dst, b, h) do { _Pragma("unroll") for (int n = 0; n < 2; ++n) _Pragma("unroll") for (int k = 0; k < 2; ++k) dst[n][k] = *(const PG8_LAS bf16x8*)(lds + PG8_SB(b, h) + boff + n * 2048 + k * 1024); } while (0)
; #define PG8_MMA(ai, bj, At, Bt) do { __builtin_amdgcn_s_setprio(1); _Pragma("unroll") for (int m = 0; m < 4; ++m) _Pragma("unroll") for (int n = 0; n < 2; ++n) _Pragma("unroll") for (int k = 0; k < 2; ++k) \
;         acc[ai][bj][m][n] = __builtin_amdgcn_mfma_f32_16x16x32_bf16(Bt[n][k], At[m][k], acc[ai][bj][m][n], 0, 0, 0); __builtin_amdgcn_s_setprio(0); } while (0)
; #define PG8_WAIT_V(n) asm volatile("s_waitcnt vmcnt(" #n ")" ::: "memory")
; #define PG8_WAIT_L(n) asm volatile("s_waitcnt lgkmcnt(" #n ")" ::: "memory")
; #define PG8_BAR __builtin_amdgcn_s_barrier()
; template <class Epi, class Sched, bool ALIGN_EPI = false, bool SP2 = false>
; __device__ __forceinline__ void gemm_phase(PG8_LAS unsigned char* lds, const Gemm g, const Sched& S, const Epi& E, const int wave_id) {
;     ...
;             const char* a1 = cA + (size_t)(t + 1) * kstep;
;             const char* a2 = last ? nA : cA + (size_t)(t + 2) * kstep; const char* b2 = last ? nB : cB + (size_t)(t + 2) * kstep;
;             const char* a3 = a2 + kstep; const char* b3 = b2 + kstep;
;             if (last && has_next) S.a_ready(nxt);
;             if constexpr (SP2) {
;             PG8_LDB(B0, 0, 0); PG8_LDB(B1, 0, 1); PG8_SCHED; PG8_LDA(At, 0, 0); PG8_STAGE(PG8_SA(1, 1), a1 + hstepA, voffA);
;             PG8_WAIT_V(8); PG8_WAIT_L(0); PG8_BAR; PG8_MMA(0, 0, At, B0); PG8_MMA(0, 1, At, B1); PG8_BAR; PG8_SCHED;
;             PG8_LDA(At, 0, 1); PG8_STAGE(PG8_SB(0, 0), b2, voffB); PG8_STAGE(PG8_SB(0, 1), b2 + hstepB, voffB); PG8_STAGE(PG8_SA(0, 0), a2, voffA);
;             PG8_WAIT_V(8); PG8_WAIT_L(0); PG8_BAR; PG8_MMA(1, 0, At, B0); PG8_MMA(1, 1, At, B1); PG8_BAR; PG8_SCHED;
.LBB0_576:
	s_add_u32 s0, s8, 0xfffc0080
	s_addc_u32 s1, s9, -1
	s_add_i32 s35, 0, 0x10000
	s_cmp_eq_u32 s5, 12
	s_cselect_b32 s29, s3, s1
	s_cselect_b32 s28, s17, s0
	v_add_u32_e32 v0, s35, v210
	s_cselect_b32 s27, s15, s4
	s_cselect_b32 s26, vcc_lo, vcc_hi
	s_add_i32 s36, 0, 0x14000
	s_waitcnt lgkmcnt(0)
	ds_read_b128 v[138:141], v0
	ds_read_b128 v[142:145], v0 offset:1024
	ds_read_b128 v[146:149], v0 offset:2048
	ds_read_b128 v[150:153], v0 offset:3072
	v_add_u32_e32 v0, s36, v210
	ds_read_b128 v[154:157], v0
	ds_read_b128 v[158:161], v0 offset:1024
	ds_read_b128 v[162:165], v0 offset:2048
	ds_read_b128 v[166:169], v0 offset:3072
	v_lshl_add_u64 v[206:207], s[8:9], 0, v[186:187]
	s_add_i32 m0, s25, 0xc000
	ds_read_b128 v[190:193], v215
	ds_read_b128 v[194:197], v215 offset:1024
	ds_read_b128 v[198:201], v215 offset:2048
	ds_read_b128 v[202:205], v215 offset:3072
	ds_read_b128 v[216:219], v215 offset:4096
	ds_read_b128 v[220:223], v215 offset:5120
	ds_read_b128 v[240:243], v215 offset:6144
	ds_read_b128 v[244:247], v215 offset:7168
	global_load_lds_dwordx4 v[206:207], off
	v_lshl_add_u64 v[206:207], s[8:9], 0, v[188:189]
	s_add_i32 m0, s25, 0xe000
	s_nop 0
	global_load_lds_dwordx4 v[206:207], off
	s_waitcnt vmcnt(24)
	s_cmp_eq_u32 s98, 1
	s_cbranch_scc1 .Lrw_3
	s_waitcnt vmcnt(8)
.Lrw_3:
	s_waitcnt lgkmcnt(0)
	s_barrier
	s_setprio 1
	s_waitcnt lgkmcnt(0)
	v_mfma_f32_16x16x32_bf16 v[134:137], v[138:141], v[190:193], v[134:137]
	v_mfma_f32_16x16x32_bf16 v[130:133], v[146:149], v[190:193], v[130:133]
	v_mfma_f32_16x16x32_bf16 v[122:125], v[138:141], v[198:201], v[122:125]
	v_mfma_f32_16x16x32_bf16 v[114:117], v[146:149], v[198:201], v[114:117]
	v_mfma_f32_16x16x32_bf16 v[106:109], v[138:141], v[216:219], v[106:109]
	v_mfma_f32_16x16x32_bf16 v[98:101], v[146:149], v[216:219], v[98:101]
	v_mfma_f32_16x16x32_bf16 v[90:93], v[138:141], v[240:243], v[90:93]
	v_mfma_f32_16x16x32_bf16 v[82:85], v[146:149], v[240:243], v[82:85]
	v_mfma_f32_16x16x32_bf16 v[134:137], v[142:145], v[194:197], v[134:137]
	v_mfma_f32_16x16x32_bf16 v[130:133], v[150:153], v[194:197], v[130:133]
	v_mfma_f32_16x16x32_bf16 v[122:125], v[142:145], v[202:205], v[122:125]
	v_mfma_f32_16x16x32_bf16 v[114:117], v[150:153], v[202:205], v[114:117]
	v_mfma_f32_16x16x32_bf16 v[106:109], v[142:145], v[220:223], v[106:109]
	v_mfma_f32_16x16x32_bf16 v[98:101], v[150:153], v[220:223], v[98:101]
	v_mfma_f32_16x16x32_bf16 v[90:93], v[142:145], v[244:247], v[90:93]
	v_mfma_f32_16x16x32_bf16 v[82:85], v[150:153], v[244:247], v[82:85]
	s_setprio 0
	s_setprio 1
	v_mfma_f32_16x16x32_bf16 v[126:129], v[154:157], v[190:193], v[126:129]
	v_mfma_f32_16x16x32_bf16 v[118:121], v[162:165], v[190:193], v[118:121]
	v_mfma_f32_16x16x32_bf16 v[110:113], v[154:157], v[198:201], v[110:113]
	v_mfma_f32_16x16x32_bf16 v[102:105], v[162:165], v[198:201], v[102:105]
	v_mfma_f32_16x16x32_bf16 v[94:97], v[154:157], v[216:219], v[94:97]
	v_mfma_f32_16x16x32_bf16 v[86:89], v[162:165], v[216:219], v[86:89]
	v_mfma_f32_16x16x32_bf16 v[78:81], v[154:157], v[240:243], v[78:81]
	v_mfma_f32_16x16x32_bf16 v[74:77], v[162:165], v[240:243], v[74:77]
	v_mfma_f32_16x16x32_bf16 v[126:129], v[158:161], v[194:197], v[126:129]
	v_mfma_f32_16x16x32_bf16 v[118:121], v[166:169], v[194:197], v[118:121]
	v_mfma_f32_16x16x32_bf16 v[110:113], v[158:161], v[202:205], v[110:113]
	v_mfma_f32_16x16x32_bf16 v[102:105], v[166:169], v[202:205], v[102:105]
	v_mfma_f32_16x16x32_bf16 v[94:97], v[158:161], v[220:223], v[94:97]
	v_mfma_f32_16x16x32_bf16 v[86:89], v[166:169], v[220:223], v[86:89]
	v_mfma_f32_16x16x32_bf16 v[78:81], v[158:161], v[244:247], v[78:81]
	v_mfma_f32_16x16x32_bf16 v[74:77], v[166:169], v[244:247], v[74:77]
	s_setprio 0
	s_barrier
	s_add_i32 s0, s35, s23
	v_lshl_add_u64 v[206:207], s[26:27], 0, v[180:181]
	s_mov_b32 m0, s0
	ds_read_b128 v[190:193], v215 offset:16384
	ds_read_b128 v[194:197], v215 offset:17408
	ds_read_b128 v[198:201], v215 offset:18432
	ds_read_b128 v[202:205], v215 offset:19456
	ds_read_b128 v[216:219], v215 offset:20480
	ds_read_b128 v[220:223], v215 offset:21504
	ds_read_b128 v[240:243], v215 offset:22528
	ds_read_b128 v[244:247], v215 offset:23552
	global_load_lds_dwordx4 v[206:207], off
	s_add_i32 m0, s0, 0x2000
	s_add_u32 s0, s26, 0x40000
	v_lshl_add_u64 v[224:225], s[26:27], 0, v[184:185]
	s_addc_u32 s1, s27, 0
	s_add_i32 s35, s36, s23
	global_load_lds_dwordx4 v[224:225], off
	v_lshl_add_u64 v[234:235], s[0:1], 0, v[180:181]
	s_mov_b32 m0, s35
	v_lshl_add_u64 v[236:237], s[28:29], 0, v[182:183]
	global_load_lds_dwordx4 v[234:235], off
	v_lshl_add_u64 v[234:235], s[0:1], 0, v[184:185]
	s_add_i32 m0, s35, 0x2000
	s_nop 0
	global_load_lds_dwordx4 v[234:235], off
	v_lshl_add_u64 v[234:235], s[28:29], 0, v[178:179]
	s_mov_b32 m0, s25
	s_nop 0
	global_load_lds_dwordx4 v[234:235], off
	s_mov_b32 m0, s30
	s_nop 0
	global_load_lds_dwordx4 v[236:237], off
	s_waitcnt vmcnt(24)
	s_cmp_eq_u32 s98, 1
	s_cbranch_scc1 .Lrw_4
	s_waitcnt vmcnt(8)
; #define PG8_STAGE(bufoff, gbase, voff) do { _Pragma("unroll") for (int _i = 0; _i < 2; ++_i) \
;         __builtin_amdgcn_global_load_lds((const unsigned*)((const char*)(gbase) + (voff)[_i]), (PG8_LAS unsigned*)(lds + (bufoff) + ldsw + _i * 8192), 16, 0, 0); } while (0)
; #define PG8_LDA(dst, b, h) do { _Pragma("unroll") for (int m = 0; m < 4; ++m) _Pragma("unroll") for (int k = 0; k < 2; ++k) dst[m][k] = *(const PG8_LAS bf16x8*)(lds + PG8_SA(b, h) + aoff + m * 2048 + k * 1024); } while (0)
; #define PG8_LDB(dst, b, h) do { _Pragma("unroll") for (int n = 0; n < 2; ++n) _Pragma("unroll") for (int k = 0; k < 2; ++k) dst[n][k] = *(const PG8_LAS bf16x8*)(lds + PG8_SB(b, h) + boff + n * 2048 + k * 1024); } while (0)
; #define PG8_MMA(ai, bj, At, Bt) do { __builtin_amdgcn_s_setprio(1); _Pragma("unroll") for (int m = 0; m < 4; ++m) _Pragma("unroll") for (int n = 0; n < 2; ++n) _Pragma("unroll") for (int k = 0; k < 2; ++k) \
;         acc[ai][bj][m][n] = __builtin_amdgcn_mfma_f32_16x16x32_bf16(Bt[n][k], At[m][k], acc[ai][bj][m][n], 0, 0, 0); __builtin_amdgcn_s_setprio(0); } while (0)
; #define PG8_WAIT_V(n) asm volatile("s_waitcnt vmcnt(" #n ")" ::: "memory")
; #define PG8_WAIT_L(n) asm volatile("s_waitcnt lgkmcnt(" #n ")" ::: "memory")
; #define PG8_BAR __builtin_amdgcn_s_barrier()
; #define PG8_SCHED __builtin_amdgcn_sched_barrier(0)
; template <class Epi, class Sched, bool ALIGN_EPI = false, bool SP2 = false>
; __device__ __forceinline__ void gemm_phase(PG8_LAS unsigned char* lds, const Gemm g, const Sched& S, const Epi& E, const int wave_id) {
;     ...
;             PG8_WAIT_V(8); PG8_WAIT_L(0); PG8_BAR; PG8_MMA(1, 0, At, B0); PG8_MMA(1, 1, At, B1); PG8_BAR; PG8_SCHED;
;             PG8_LDB(B0, 1, 0); PG8_LDB(B1, 1, 1); PG8_SCHED; PG8_LDA(At, 1, 0); PG8_STAGE(PG8_SA(0, 1), a2 + hstepA, voffA);
;             PG8_WAIT_V(8); PG8_WAIT_L(0); PG8_BAR; PG8_MMA(0, 0, At, B0); PG8_MMA(0, 1, At, B1); PG8_BAR; PG8_SCHED;
.Lrw_4:
	s_mov_b32 s98, 0
	s_waitcnt lgkmcnt(0)
	s_barrier
	s_setprio 1
	s_waitcnt lgkmcnt(0)
	v_mfma_f32_16x16x32_bf16 v[70:73], v[138:141], v[190:193], v[70:73]
	v_mfma_f32_16x16x32_bf16 v[66:69], v[146:149], v[190:193], v[66:69]
	v_mfma_f32_16x16x32_bf16 v[58:61], v[138:141], v[198:201], v[58:61]
	v_mfma_f32_16x16x32_bf16 v[50:53], v[146:149], v[198:201], v[50:53]
	v_mfma_f32_16x16x32_bf16 v[42:45], v[138:141], v[216:219], v[42:45]
	v_mfma_f32_16x16x32_bf16 v[34:37], v[146:149], v[216:219], v[34:37]
	v_mfma_f32_16x16x32_bf16 v[26:29], v[138:141], v[240:243], v[26:29]
	v_mfma_f32_16x16x32_bf16 v[18:21], v[146:149], v[240:243], v[18:21]
	v_mfma_f32_16x16x32_bf16 v[70:73], v[142:145], v[194:197], v[70:73]
	v_mfma_f32_16x16x32_bf16 v[66:69], v[150:153], v[194:197], v[66:69]
	v_mfma_f32_16x16x32_bf16 v[58:61], v[142:145], v[202:205], v[58:61]
	v_mfma_f32_16x16x32_bf16 v[50:53], v[150:153], v[202:205], v[50:53]
	v_mfma_f32_16x16x32_bf16 v[42:45], v[142:145], v[220:223], v[42:45]
	v_mfma_f32_16x16x32_bf16 v[34:37], v[150:153], v[220:223], v[34:37]
	v_mfma_f32_16x16x32_bf16 v[26:29], v[142:145], v[244:247], v[26:29]
	v_mfma_f32_16x16x32_bf16 v[18:21], v[150:153], v[244:247], v[18:21]
	s_setprio 0
	s_setprio 1
	v_mfma_f32_16x16x32_bf16 v[62:65], v[154:157], v[190:193], v[62:65]
	v_mfma_f32_16x16x32_bf16 v[54:57], v[162:165], v[190:193], v[54:57]
	v_mfma_f32_16x16x32_bf16 v[46:49], v[154:157], v[198:201], v[46:49]
	v_mfma_f32_16x16x32_bf16 v[38:41], v[162:165], v[198:201], v[38:41]
	v_mfma_f32_16x16x32_bf16 v[30:33], v[154:157], v[216:219], v[30:33]
	v_mfma_f32_16x16x32_bf16 v[22:25], v[162:165], v[216:219], v[22:25]
	v_mfma_f32_16x16x32_bf16 v[14:17], v[154:157], v[240:243], v[14:17]
	v_mfma_f32_16x16x32_bf16 v[10:13], v[162:165], v[240:243], v[10:13]
	v_mfma_f32_16x16x32_bf16 v[62:65], v[158:161], v[194:197], v[62:65]
	v_mfma_f32_16x16x32_bf16 v[54:57], v[166:169], v[194:197], v[54:57]
	v_mfma_f32_16x16x32_bf16 v[46:49], v[158:161], v[202:205], v[46:49]
	v_mfma_f32_16x16x32_bf16 v[38:41], v[166:169], v[202:205], v[38:41]
	v_mfma_f32_16x16x32_bf16 v[30:33], v[158:161], v[220:223], v[30:33]
	v_mfma_f32_16x16x32_bf16 v[22:25], v[166:169], v[220:223], v[22:25]
	v_mfma_f32_16x16x32_bf16 v[14:17], v[158:161], v[244:247], v[14:17]
	v_mfma_f32_16x16x32_bf16 v[10:13], v[166:169], v[244:247], v[10:13]
	s_setprio 0
	s_barrier
	s_add_i32 s35, 0, 0x18000
	v_add_u32_e32 v0, s35, v210
	s_add_i32 s36, 0, 0x1c000
	ds_read_b128 v[138:141], v0
	ds_read_b128 v[142:145], v0 offset:1024
	ds_read_b128 v[146:149], v0 offset:2048
	ds_read_b128 v[150:153], v0 offset:3072
	v_add_u32_e32 v0, s36, v210
	ds_read_b128 v[154:157], v0
	ds_read_b128 v[158:161], v0 offset:1024
	ds_read_b128 v[162:165], v0 offset:2048
	ds_read_b128 v[166:169], v0 offset:3072
	s_add_u32 s0, s28, 0x40000
	s_addc_u32 s1, s29, 0
	s_mov_b32 m0, s31
	v_lshl_add_u64 v[248:249], s[0:1], 0, v[178:179]
	ds_read_b128 v[190:193], v215 offset:32768
	ds_read_b128 v[194:197], v215 offset:33792
	ds_read_b128 v[198:201], v215 offset:34816
	ds_read_b128 v[202:205], v215 offset:35840
	ds_read_b128 v[216:219], v215 offset:36864
	ds_read_b128 v[220:223], v215 offset:37888
	ds_read_b128 v[240:243], v215 offset:38912
	ds_read_b128 v[244:247], v215 offset:39936
	global_load_lds_dwordx4 v[248:249], off
	v_lshl_add_u64 v[248:249], s[0:1], 0, v[182:183]
	s_mov_b32 m0, s34
	s_nop 0
	global_load_lds_dwordx4 v[248:249], off
	s_waitcnt vmcnt(8)
	s_waitcnt lgkmcnt(0)
	s_barrier
	s_setprio 1
	s_waitcnt lgkmcnt(0)
	v_mfma_f32_16x16x32_bf16 v[134:137], v[138:141], v[190:193], v[134:137]
	v_mfma_f32_16x16x32_bf16 v[130:133], v[146:149], v[190:193], v[130:133]
	v_mfma_f32_16x16x32_bf16 v[122:125], v[138:141], v[198:201], v[122:125]
	v_mfma_f32_16x16x32_bf16 v[114:117], v[146:149], v[198:201], v[114:117]
	v_mfma_f32_16x16x32_bf16 v[106:109], v[138:141], v[216:219], v[106:109]
	v_mfma_f32_16x16x32_bf16 v[98:101], v[146:149], v[216:219], v[98:101]
	v_mfma_f32_16x16x32_bf16 v[90:93], v[138:141], v[240:243], v[90:93]
	v_mfma_f32_16x16x32_bf16 v[82:85], v[146:149], v[240:243], v[82:85]
	v_mfma_f32_16x16x32_bf16 v[134:137], v[142:145], v[194:197], v[134:137]
	v_mfma_f32_16x16x32_bf16 v[130:133], v[150:153], v[194:197], v[130:133]
	v_mfma_f32_16x16x32_bf16 v[122:125], v[142:145], v[202:205], v[122:125]
	v_mfma_f32_16x16x32_bf16 v[114:117], v[150:153], v[202:205], v[114:117]
	v_mfma_f32_16x16x32_bf16 v[106:109], v[142:145], v[220:223], v[106:109]
	v_mfma_f32_16x16x32_bf16 v[98:101], v[150:153], v[220:223], v[98:101]
	v_mfma_f32_16x16x32_bf16 v[90:93], v[142:145], v[244:247], v[90:93]
	v_mfma_f32_16x16x32_bf16 v[82:85], v[150:153], v[244:247], v[82:85]
	s_setprio 0
	s_setprio 1
	v_mfma_f32_16x16x32_bf16 v[126:129], v[154:157], v[190:193], v[126:129]
	v_mfma_f32_16x16x32_bf16 v[118:121], v[162:165], v[190:193], v[118:121]
	v_mfma_f32_16x16x32_bf16 v[110:113], v[154:157], v[198:201], v[110:113]
	v_mfma_f32_16x16x32_bf16 v[102:105], v[162:165], v[198:201], v[102:105]
	v_mfma_f32_16x16x32_bf16 v[94:97], v[154:157], v[216:219], v[94:97]
	v_mfma_f32_16x16x32_bf16 v[86:89], v[162:165], v[216:219], v[86:89]
	v_mfma_f32_16x16x32_bf16 v[78:81], v[154:157], v[240:243], v[78:81]
	v_mfma_f32_16x16x32_bf16 v[74:77], v[162:165], v[240:243], v[74:77]
	v_mfma_f32_16x16x32_bf16 v[126:129], v[158:161], v[194:197], v[126:129]
	v_mfma_f32_16x16x32_bf16 v[118:121], v[166:169], v[194:197], v[118:121]
	v_mfma_f32_16x16x32_bf16 v[110:113], v[158:161], v[202:205], v[110:113]
	v_mfma_f32_16x16x32_bf16 v[102:105], v[166:169], v[202:205], v[102:105]
	v_mfma_f32_16x16x32_bf16 v[94:97], v[158:161], v[220:223], v[94:97]
	v_mfma_f32_16x16x32_bf16 v[86:89], v[166:169], v[220:223], v[86:89]
	v_mfma_f32_16x16x32_bf16 v[78:81], v[158:161], v[244:247], v[78:81]
	v_mfma_f32_16x16x32_bf16 v[74:77], v[166:169], v[244:247], v[74:77]
	s_setprio 0
	s_barrier
; #define PG8_STAGE(bufoff, gbase, voff) do { _Pragma("unroll") for (int _i = 0; _i < 2; ++_i) \
;         __builtin_amdgcn_global_load_lds((const unsigned*)((const char*)(gbase) + (voff)[_i]), (PG8_LAS unsigned*)(lds + (bufoff) + ldsw + _i * 8192), 16, 0, 0); } while (0)
; #define PG8_LDA(dst, b, h) do { _Pragma("unroll") for (int m = 0; m < 4; ++m) _Pragma("unroll") for (int k = 0; k < 2; ++k) dst[m][k] = *(const PG8_LAS bf16x8*)(lds + PG8_SA(b, h) + aoff + m * 2048 + k * 1024); } while (0)
; #define PG8_MMA(ai, bj, At, Bt) do { __builtin_amdgcn_s_setprio(1); _Pragma("unroll") for (int m = 0; m < 4; ++m) _Pragma("unroll") for (int n = 0; n < 2; ++n) _Pragma("unroll") for (int k = 0; k < 2; ++k) \
;         acc[ai][bj][m][n] = __builtin_amdgcn_mfma_f32_16x16x32_bf16(Bt[n][k], At[m][k], acc[ai][bj][m][n], 0, 0, 0); __builtin_amdgcn_s_setprio(0); } while (0)
; #define PG8_WAIT_V(n) asm volatile("s_waitcnt vmcnt(" #n ")" ::: "memory")
; #define PG8_WAIT_L(n) asm volatile("s_waitcnt lgkmcnt(" #n ")" ::: "memory")
; #define PG8_BAR __builtin_amdgcn_s_barrier()
; #define PG8_SCHED __builtin_amdgcn_sched_barrier(0)
; template <class Epi, class Sched, bool ALIGN_EPI = false, bool SP2 = false>
; __device__ __forceinline__ void gemm_phase(PG8_LAS unsigned char* lds, const Gemm g, const Sched& S, const Epi& E, const int wave_id) {
;     ...
;         for (int t = 0; t < nt; t += 2) {
;             const bool last = (t == nt - 2);
;     ...
;             PG8_LDA(At, 1, 1); PG8_STAGE(PG8_SB(1, 0), b3, voffB); PG8_STAGE(PG8_SB(1, 1), b3 + hstepB, voffB); PG8_STAGE(PG8_SA(1, 0), a3, voffA);
;             PG8_WAIT_V(8); PG8_WAIT_L(0); PG8_BAR; PG8_MMA(1, 0, At, B0); PG8_MMA(1, 1, At, B1); PG8_BAR; PG8_SCHED;
	s_add_i32 s0, s35, s23
	v_lshl_add_u64 v[206:207], v[206:207], 0, s[62:63]
	s_mov_b32 m0, s0
	ds_read_b128 v[190:193], v215 offset:49152
	ds_read_b128 v[194:197], v215 offset:50176
	ds_read_b128 v[198:201], v215 offset:51200
	ds_read_b128 v[202:205], v215 offset:52224
	ds_read_b128 v[216:219], v215 offset:53248
	ds_read_b128 v[220:223], v215 offset:54272
	ds_read_b128 v[240:243], v215 offset:55296
	ds_read_b128 v[244:247], v215 offset:56320
	global_load_lds_dwordx4 v[206:207], off
	s_add_i32 m0, s0, 0x2000
	s_add_u32 s0, s26, 0x40080
	v_lshl_add_u64 v[206:207], v[224:225], 0, s[62:63]
	s_addc_u32 s1, s27, 0
	s_add_i32 s26, s36, s23
	global_load_lds_dwordx4 v[206:207], off
	v_lshl_add_u64 v[206:207], s[0:1], 0, v[180:181]
	s_mov_b32 m0, s26
	s_nop 0
	global_load_lds_dwordx4 v[206:207], off
	v_lshl_add_u64 v[206:207], s[0:1], 0, v[184:185]
	s_add_i32 m0, s26, 0x2000
	s_nop 0
	global_load_lds_dwordx4 v[206:207], off
	v_lshl_add_u64 v[206:207], v[234:235], 0, s[62:63]
	s_mov_b32 m0, s44
	s_nop 0
	global_load_lds_dwordx4 v[206:207], off
	v_lshl_add_u64 v[206:207], v[236:237], 0, s[62:63]
	s_mov_b32 m0, s45
	s_nop 0
	global_load_lds_dwordx4 v[206:207], off
	s_waitcnt vmcnt(8)
	s_waitcnt lgkmcnt(0)
	s_barrier
	s_setprio 1
	s_waitcnt lgkmcnt(0)
	v_mfma_f32_16x16x32_bf16 v[70:73], v[138:141], v[190:193], v[70:73]
	v_mfma_f32_16x16x32_bf16 v[66:69], v[146:149], v[190:193], v[66:69]
	v_mfma_f32_16x16x32_bf16 v[58:61], v[138:141], v[198:201], v[58:61]
	v_mfma_f32_16x16x32_bf16 v[50:53], v[146:149], v[198:201], v[50:53]
	v_mfma_f32_16x16x32_bf16 v[42:45], v[138:141], v[216:219], v[42:45]
	v_mfma_f32_16x16x32_bf16 v[34:37], v[146:149], v[216:219], v[34:37]
	v_mfma_f32_16x16x32_bf16 v[26:29], v[138:141], v[240:243], v[26:29]
	v_mfma_f32_16x16x32_bf16 v[18:21], v[146:149], v[240:243], v[18:21]
	v_mfma_f32_16x16x32_bf16 v[70:73], v[142:145], v[194:197], v[70:73]
	v_mfma_f32_16x16x32_bf16 v[66:69], v[150:153], v[194:197], v[66:69]
	v_mfma_f32_16x16x32_bf16 v[58:61], v[142:145], v[202:205], v[58:61]
	v_mfma_f32_16x16x32_bf16 v[50:53], v[150:153], v[202:205], v[50:53]
	v_mfma_f32_16x16x32_bf16 v[42:45], v[142:145], v[220:223], v[42:45]
	v_mfma_f32_16x16x32_bf16 v[34:37], v[150:153], v[220:223], v[34:37]
	v_mfma_f32_16x16x32_bf16 v[26:29], v[142:145], v[244:247], v[26:29]
	v_mfma_f32_16x16x32_bf16 v[18:21], v[150:153], v[244:247], v[18:21]
	s_setprio 0
	s_setprio 1
	v_mfma_f32_16x16x32_bf16 v[62:65], v[154:157], v[190:193], v[62:65]
	v_mfma_f32_16x16x32_bf16 v[54:57], v[162:165], v[190:193], v[54:57]
	v_mfma_f32_16x16x32_bf16 v[46:49], v[154:157], v[198:201], v[46:49]
	v_mfma_f32_16x16x32_bf16 v[38:41], v[162:165], v[198:201], v[38:41]
	v_mfma_f32_16x16x32_bf16 v[30:33], v[154:157], v[216:219], v[30:33]
	v_mfma_f32_16x16x32_bf16 v[22:25], v[162:165], v[216:219], v[22:25]
	v_mfma_f32_16x16x32_bf16 v[14:17], v[154:157], v[240:243], v[14:17]
	v_mfma_f32_16x16x32_bf16 v[10:13], v[162:165], v[240:243], v[10:13]
	v_mfma_f32_16x16x32_bf16 v[62:65], v[158:161], v[194:197], v[62:65]
	v_mfma_f32_16x16x32_bf16 v[54:57], v[166:169], v[194:197], v[54:57]
	v_mfma_f32_16x16x32_bf16 v[46:49], v[158:161], v[202:205], v[46:49]
	v_mfma_f32_16x16x32_bf16 v[38:41], v[166:169], v[202:205], v[38:41]
	v_mfma_f32_16x16x32_bf16 v[30:33], v[158:161], v[220:223], v[30:33]
	v_mfma_f32_16x16x32_bf16 v[22:25], v[166:169], v[220:223], v[22:25]
	v_mfma_f32_16x16x32_bf16 v[14:17], v[158:161], v[244:247], v[14:17]
	v_mfma_f32_16x16x32_bf16 v[10:13], v[166:169], v[244:247], v[10:13]
	s_setprio 0
	s_barrier
	s_add_i32 s5, s5, 2
	s_add_u32 s8, s8, 0x100
	s_addc_u32 s9, s9, 0
	s_add_u32 vcc_hi, vcc_hi, 0x100
	s_addc_u32 s4, s4, 0
	s_cmp_gt_u32 s5, 13
	s_cbranch_scc0 .LBB0_576
	s_and_b64 vcc, exec, s[10:11]
	s_cbranch_vccz .LBB0_579
	s_barrier

.LBB0_590:
	ds_read_b128 v[162:165], v214 offset:512
	ds_read_b128 v[154:157], v214 offset:528
	ds_read_b128 v[166:169], v213 offset:512
	ds_read_b128 v[158:161], v213 offset:528
	s_lshl_b32 s0, s22, 8
	s_waitcnt lgkmcnt(0)
	v_pk_fma_f32 v[216:217], v[150:151], v[206:207], v[134:135] op_sel_hi:[1,0,1] neg_lo:[1,0,0] neg_hi:[1,0,0]
	s_add_i32 s0, s0, s39
	v_xor_b32_e32 v135, 0x80000000, v153
	v_xor_b32_e32 v134, 0x80000000, v152
	v_pk_fma_f32 v[152:153], v[206:207], v[216:217], v[146:147] op_sel:[1,0,0]
	v_pk_fma_f32 v[216:217], v[142:143], v[206:207], v[130:131] op_sel_hi:[1,0,1] neg_lo:[1,0,0] neg_hi:[1,0,0]
	v_xor_b32_e32 v131, 0x80000000, v145
	v_xor_b32_e32 v130, 0x80000000, v144
	v_lshl_or_b32 v0, s24, 8, v211
	v_add_u32_e32 v204, s0, v204
	s_movk_i32 s0, 0x1800
	v_pk_fma_f32 v[132:133], v[130:131], v[206:207], v[132:133] op_sel_hi:[1,0,1]
	v_mad_u64_u32 v[204:205], s[0:1], v204, s0, v[0:1]
	v_pk_fma_f32 v[132:133], v[206:207], v[132:133], v[140:141] op_sel:[1,0,0]
	v_pk_fma_f32 v[126:127], v[206:207], v[166:167], v[126:127] op_sel_hi:[0,1,1] neg_lo:[1,0,0] neg_hi:[1,0,0]
	v_pk_fma_f32 v[128:129], v[206:207], v[168:169], v[128:129] op_sel_hi:[0,1,1] neg_lo:[1,0,0] neg_hi:[1,0,0]
	v_pk_fma_f32 v[118:119], v[206:207], v[158:159], v[118:119] op_sel_hi:[0,1,1] neg_lo:[1,0,0] neg_hi:[1,0,0]
	v_pk_fma_f32 v[120:121], v[206:207], v[160:161], v[120:121] op_sel_hi:[0,1,1] neg_lo:[1,0,0] neg_hi:[1,0,0]
	v_mov_b32_e32 v205, v1
	v_cvt_pk_bf16_f32 v219, v132, v133
	v_pk_fma_f32 v[128:129], v[206:207], v[128:129], v[164:165] op_sel:[1,0,0]
	v_pk_fma_f32 v[126:127], v[206:207], v[126:127], v[162:163] op_sel:[1,0,0]
	v_pk_fma_f32 v[132:133], v[206:207], v[120:121], v[156:157] op_sel:[1,0,0]
	v_pk_fma_f32 v[120:121], v[206:207], v[118:119], v[154:155] op_sel:[1,0,0]
	v_lshl_add_u64 v[220:221], v[204:205], 1, s[74:75]
	v_pk_fma_f32 v[136:137], v[134:135], v[206:207], v[136:137] op_sel_hi:[1,0,1]
	v_cvt_pk_bf16_f32 v118, v126, v127
	v_cvt_pk_bf16_f32 v119, v128, v129
	v_cvt_pk_bf16_f32 v120, v120, v121
	v_cvt_pk_bf16_f32 v121, v132, v133
	v_pk_fma_f32 v[136:137], v[206:207], v[136:137], v[148:149] op_sel:[1,0,0]
	v_pk_fma_f32 v[144:145], v[206:207], v[216:217], v[138:139] op_sel:[1,0,0]
	global_store_dwordx4 v[220:221], v[118:121], off offset:256
	v_pk_fma_f32 v[114:115], v[142:143], v[202:203], v[114:115] op_sel_hi:[1,0,1] neg_lo:[1,0,0] neg_hi:[1,0,0]
	v_pk_fma_f32 v[116:117], v[130:131], v[202:203], v[116:117] op_sel_hi:[1,0,1]
	v_pk_fma_f32 v[120:121], v[150:151], v[202:203], v[122:123] op_sel_hi:[1,0,1] neg_lo:[1,0,0] neg_hi:[1,0,0]
	v_pk_fma_f32 v[122:123], v[134:135], v[202:203], v[124:125] op_sel_hi:[1,0,1]
	v_cvt_pk_bf16_f32 v216, v152, v153
	v_cvt_pk_bf16_f32 v217, v136, v137
	v_cvt_pk_bf16_f32 v218, v144, v145
	v_add_u32_e32 v0, 0x18000, v204
	v_pk_fma_f32 v[122:123], v[202:203], v[122:123], v[148:149] op_sel:[1,0,0]
	v_pk_fma_f32 v[120:121], v[202:203], v[120:121], v[146:147] op_sel:[1,0,0]
	v_pk_fma_f32 v[124:125], v[202:203], v[116:117], v[140:141] op_sel:[1,0,0]
	v_pk_fma_f32 v[116:117], v[202:203], v[114:115], v[138:139] op_sel:[1,0,0]
	global_store_dwordx4 v[220:221], v[216:219], off
	v_lshl_add_u64 v[118:119], v[0:1], 1, s[74:75]
	v_cvt_pk_bf16_f32 v114, v120, v121
	v_cvt_pk_bf16_f32 v115, v122, v123
	v_cvt_pk_bf16_f32 v116, v116, v117
	v_cvt_pk_bf16_f32 v117, v124, v125
	v_pk_fma_f32 v[110:111], v[202:203], v[166:167], v[110:111] op_sel_hi:[0,1,1] neg_lo:[1,0,0] neg_hi:[1,0,0]
	v_pk_fma_f32 v[112:113], v[202:203], v[168:169], v[112:113] op_sel_hi:[0,1,1] neg_lo:[1,0,0] neg_hi:[1,0,0]
	v_pk_fma_f32 v[102:103], v[202:203], v[158:159], v[102:103] op_sel_hi:[0,1,1] neg_lo:[1,0,0] neg_hi:[1,0,0]
	v_pk_fma_f32 v[104:105], v[202:203], v[160:161], v[104:105] op_sel_hi:[0,1,1] neg_lo:[1,0,0] neg_hi:[1,0,0]
	global_store_dwordx4 v[118:119], v[114:117], off
	v_pk_fma_f32 v[112:113], v[202:203], v[112:113], v[164:165] op_sel:[1,0,0]
	v_pk_fma_f32 v[110:111], v[202:203], v[110:111], v[162:163] op_sel:[1,0,0]
	v_pk_fma_f32 v[114:115], v[202:203], v[104:105], v[156:157] op_sel:[1,0,0]
	v_pk_fma_f32 v[104:105], v[202:203], v[102:103], v[154:155] op_sel:[1,0,0]
	v_cvt_pk_bf16_f32 v102, v110, v111
	v_cvt_pk_bf16_f32 v103, v112, v113
	v_cvt_pk_bf16_f32 v104, v104, v105
	v_cvt_pk_bf16_f32 v105, v114, v115
	global_store_dwordx4 v[118:119], v[102:105], off offset:256
	v_pk_fma_f32 v[98:99], v[142:143], v[200:201], v[98:99] op_sel_hi:[1,0,1] neg_lo:[1,0,0] neg_hi:[1,0,0]
	v_pk_fma_f32 v[100:101], v[130:131], v[200:201], v[100:101] op_sel_hi:[1,0,1]
	v_pk_fma_f32 v[104:105], v[150:151], v[200:201], v[106:107] op_sel_hi:[1,0,1] neg_lo:[1,0,0] neg_hi:[1,0,0]
	v_pk_fma_f32 v[106:107], v[134:135], v[200:201], v[108:109] op_sel_hi:[1,0,1]
	v_add_u32_e32 v0, 0x30000, v204
	v_pk_fma_f32 v[106:107], v[200:201], v[106:107], v[148:149] op_sel:[1,0,0]
	v_pk_fma_f32 v[104:105], v[200:201], v[104:105], v[146:147] op_sel:[1,0,0]
	v_pk_fma_f32 v[108:109], v[200:201], v[100:101], v[140:141] op_sel:[1,0,0]
	v_pk_fma_f32 v[100:101], v[200:201], v[98:99], v[138:139] op_sel:[1,0,0]
	v_lshl_add_u64 v[102:103], v[0:1], 1, s[74:75]
	v_cvt_pk_bf16_f32 v98, v104, v105
	v_cvt_pk_bf16_f32 v99, v106, v107
	v_cvt_pk_bf16_f32 v100, v100, v101
	v_cvt_pk_bf16_f32 v101, v108, v109
	v_pk_fma_f32 v[94:95], v[200:201], v[166:167], v[94:95] op_sel_hi:[0,1,1] neg_lo:[1,0,0] neg_hi:[1,0,0]
	v_pk_fma_f32 v[96:97], v[200:201], v[168:169], v[96:97] op_sel_hi:[0,1,1] neg_lo:[1,0,0] neg_hi:[1,0,0]
	v_pk_fma_f32 v[86:87], v[200:201], v[158:159], v[86:87] op_sel_hi:[0,1,1] neg_lo:[1,0,0] neg_hi:[1,0,0]
	v_pk_fma_f32 v[88:89], v[200:201], v[160:161], v[88:89] op_sel_hi:[0,1,1] neg_lo:[1,0,0] neg_hi:[1,0,0]
	global_store_dwordx4 v[102:103], v[98:101], off
	v_pk_fma_f32 v[96:97], v[200:201], v[96:97], v[164:165] op_sel:[1,0,0]
	v_pk_fma_f32 v[94:95], v[200:201], v[94:95], v[162:163] op_sel:[1,0,0]
	v_pk_fma_f32 v[98:99], v[200:201], v[88:89], v[156:157] op_sel:[1,0,0]
	v_pk_fma_f32 v[88:89], v[200:201], v[86:87], v[154:155] op_sel:[1,0,0]
	v_cvt_pk_bf16_f32 v86, v94, v95
	v_cvt_pk_bf16_f32 v87, v96, v97
	v_cvt_pk_bf16_f32 v88, v88, v89
	v_cvt_pk_bf16_f32 v89, v98, v99
	global_store_dwordx4 v[102:103], v[86:89], off offset:256
	v_pk_fma_f32 v[82:83], v[142:143], v[198:199], v[82:83] op_sel_hi:[1,0,1] neg_lo:[1,0,0] neg_hi:[1,0,0]
	v_pk_fma_f32 v[84:85], v[130:131], v[198:199], v[84:85] op_sel_hi:[1,0,1]
	v_pk_fma_f32 v[88:89], v[150:151], v[198:199], v[90:91] op_sel_hi:[1,0,1] neg_lo:[1,0,0] neg_hi:[1,0,0]
	v_pk_fma_f32 v[90:91], v[134:135], v[198:199], v[92:93] op_sel_hi:[1,0,1]
	v_add_u32_e32 v0, 0x48000, v204
	v_pk_fma_f32 v[90:91], v[198:199], v[90:91], v[148:149] op_sel:[1,0,0]
	v_pk_fma_f32 v[88:89], v[198:199], v[88:89], v[146:147] op_sel:[1,0,0]
	v_pk_fma_f32 v[92:93], v[198:199], v[84:85], v[140:141] op_sel:[1,0,0]
	v_pk_fma_f32 v[84:85], v[198:199], v[82:83], v[138:139] op_sel:[1,0,0]
	v_lshl_add_u64 v[86:87], v[0:1], 1, s[74:75]
	v_cvt_pk_bf16_f32 v82, v88, v89
	v_cvt_pk_bf16_f32 v83, v90, v91
	v_cvt_pk_bf16_f32 v84, v84, v85
	v_cvt_pk_bf16_f32 v85, v92, v93
	v_pk_fma_f32 v[78:79], v[198:199], v[166:167], v[78:79] op_sel_hi:[0,1,1] neg_lo:[1,0,0] neg_hi:[1,0,0]
	v_pk_fma_f32 v[80:81], v[198:199], v[168:169], v[80:81] op_sel_hi:[0,1,1] neg_lo:[1,0,0] neg_hi:[1,0,0]
	v_pk_fma_f32 v[74:75], v[198:199], v[158:159], v[74:75] op_sel_hi:[0,1,1] neg_lo:[1,0,0] neg_hi:[1,0,0]
	v_pk_fma_f32 v[76:77], v[198:199], v[160:161], v[76:77] op_sel_hi:[0,1,1] neg_lo:[1,0,0] neg_hi:[1,0,0]
	global_store_dwordx4 v[86:87], v[82:85], off
	v_pk_fma_f32 v[80:81], v[198:199], v[80:81], v[164:165] op_sel:[1,0,0]
	v_pk_fma_f32 v[78:79], v[198:199], v[78:79], v[162:163] op_sel:[1,0,0]
	v_pk_fma_f32 v[82:83], v[198:199], v[76:77], v[156:157] op_sel:[1,0,0]
	v_pk_fma_f32 v[76:77], v[198:199], v[74:75], v[154:155] op_sel:[1,0,0]
	v_cvt_pk_bf16_f32 v74, v78, v79
	v_cvt_pk_bf16_f32 v75, v80, v81
	v_cvt_pk_bf16_f32 v76, v76, v77
	v_cvt_pk_bf16_f32 v77, v82, v83
	v_pk_fma_f32 v[70:71], v[150:151], v[196:197], v[70:71] op_sel_hi:[1,0,1] neg_lo:[1,0,0] neg_hi:[1,0,0]
	v_pk_fma_f32 v[72:73], v[134:135], v[196:197], v[72:73] op_sel_hi:[1,0,1]
	v_pk_fma_f32 v[66:67], v[142:143], v[196:197], v[66:67] op_sel_hi:[1,0,1] neg_lo:[1,0,0] neg_hi:[1,0,0]
	v_pk_fma_f32 v[68:69], v[130:131], v[196:197], v[68:69] op_sel_hi:[1,0,1]
	global_store_dwordx4 v[86:87], v[74:77], off offset:256
	v_add_u32_e32 v0, 0xc0000, v204
	v_pk_fma_f32 v[72:73], v[196:197], v[72:73], v[148:149] op_sel:[1,0,0]
	v_pk_fma_f32 v[70:71], v[196:197], v[70:71], v[146:147] op_sel:[1,0,0]
	v_pk_fma_f32 v[76:77], v[196:197], v[68:69], v[140:141] op_sel:[1,0,0]
	v_pk_fma_f32 v[68:69], v[196:197], v[66:67], v[138:139] op_sel:[1,0,0]
	v_lshl_add_u64 v[74:75], v[0:1], 1, s[74:75]
	v_cvt_pk_bf16_f32 v66, v70, v71
	v_cvt_pk_bf16_f32 v67, v72, v73
	v_cvt_pk_bf16_f32 v68, v68, v69
	v_cvt_pk_bf16_f32 v69, v76, v77
	v_pk_fma_f32 v[62:63], v[196:197], v[166:167], v[62:63] op_sel_hi:[0,1,1] neg_lo:[1,0,0] neg_hi:[1,0,0]
	v_pk_fma_f32 v[64:65], v[196:197], v[168:169], v[64:65] op_sel_hi:[0,1,1] neg_lo:[1,0,0] neg_hi:[1,0,0]
	v_pk_fma_f32 v[54:55], v[196:197], v[158:159], v[54:55] op_sel_hi:[0,1,1] neg_lo:[1,0,0] neg_hi:[1,0,0]
	v_pk_fma_f32 v[56:57], v[196:197], v[160:161], v[56:57] op_sel_hi:[0,1,1] neg_lo:[1,0,0] neg_hi:[1,0,0]
	global_store_dwordx4 v[74:75], v[66:69], off
	v_pk_fma_f32 v[64:65], v[196:197], v[64:65], v[164:165] op_sel:[1,0,0]
	v_pk_fma_f32 v[62:63], v[196:197], v[62:63], v[162:163] op_sel:[1,0,0]
	v_pk_fma_f32 v[66:67], v[196:197], v[56:57], v[156:157] op_sel:[1,0,0]
	v_pk_fma_f32 v[56:57], v[196:197], v[54:55], v[154:155] op_sel:[1,0,0]
	v_cvt_pk_bf16_f32 v54, v62, v63
	v_cvt_pk_bf16_f32 v55, v64, v65
	v_cvt_pk_bf16_f32 v56, v56, v57
	v_cvt_pk_bf16_f32 v57, v66, v67
	global_store_dwordx4 v[74:75], v[54:57], off offset:256
	v_pk_fma_f32 v[50:51], v[142:143], v[194:195], v[50:51] op_sel_hi:[1,0,1] neg_lo:[1,0,0] neg_hi:[1,0,0]
	v_pk_fma_f32 v[52:53], v[130:131], v[194:195], v[52:53] op_sel_hi:[1,0,1]
	v_pk_fma_f32 v[56:57], v[150:151], v[194:195], v[58:59] op_sel_hi:[1,0,1] neg_lo:[1,0,0] neg_hi:[1,0,0]
	v_pk_fma_f32 v[58:59], v[134:135], v[194:195], v[60:61] op_sel_hi:[1,0,1]
	v_add_u32_e32 v0, 0xd8000, v204
	v_pk_fma_f32 v[58:59], v[194:195], v[58:59], v[148:149] op_sel:[1,0,0]
	v_pk_fma_f32 v[56:57], v[194:195], v[56:57], v[146:147] op_sel:[1,0,0]
	v_pk_fma_f32 v[60:61], v[194:195], v[52:53], v[140:141] op_sel:[1,0,0]
	v_pk_fma_f32 v[52:53], v[194:195], v[50:51], v[138:139] op_sel:[1,0,0]
	v_lshl_add_u64 v[54:55], v[0:1], 1, s[74:75]
	v_cvt_pk_bf16_f32 v50, v56, v57
	v_cvt_pk_bf16_f32 v51, v58, v59
	v_cvt_pk_bf16_f32 v52, v52, v53
	v_cvt_pk_bf16_f32 v53, v60, v61
; template <class Epi, class Sched, bool ALIGN_EPI = false, bool SP2 = false>
; __device__ __forceinline__ void gemm_phase(PG8_LAS unsigned char* lds, const Gemm g, const Sched& S, const Epi& E, const int wave_id) {
;     ...
;         if (!has_next) break;
; #pragma unroll
;         for (int a = 0; a < 2; ++a)
; #pragma unroll
;             for (int b = 0; b < 2; ++b)
; #pragma unroll
;                 for (int m = 0; m < 4; ++m)
; #pragma unroll
;                     for (int n = 0; n < 2; ++n) acc[a][b][m][n] = (f32x4){0.f, 0.f, 0.f, 0.f};
;         cur = nxt; cA = nA; cB = nB; ++ui;
;         if constexpr (Epi::HAS_PF) E.prefetch(cur, tid);
	v_pk_fma_f32 v[46:47], v[194:195], v[166:167], v[46:47] op_sel_hi:[0,1,1] neg_lo:[1,0,0] neg_hi:[1,0,0]
	v_pk_fma_f32 v[48:49], v[194:195], v[168:169], v[48:49] op_sel_hi:[0,1,1] neg_lo:[1,0,0] neg_hi:[1,0,0]
	v_pk_fma_f32 v[38:39], v[194:195], v[158:159], v[38:39] op_sel_hi:[0,1,1] neg_lo:[1,0,0] neg_hi:[1,0,0]
	v_pk_fma_f32 v[40:41], v[194:195], v[160:161], v[40:41] op_sel_hi:[0,1,1] neg_lo:[1,0,0] neg_hi:[1,0,0]
	global_store_dwordx4 v[54:55], v[50:53], off
	v_pk_fma_f32 v[48:49], v[194:195], v[48:49], v[164:165] op_sel:[1,0,0]
	v_pk_fma_f32 v[46:47], v[194:195], v[46:47], v[162:163] op_sel:[1,0,0]
	v_pk_fma_f32 v[50:51], v[194:195], v[40:41], v[156:157] op_sel:[1,0,0]
	v_pk_fma_f32 v[40:41], v[194:195], v[38:39], v[154:155] op_sel:[1,0,0]
	v_cvt_pk_bf16_f32 v38, v46, v47
	v_cvt_pk_bf16_f32 v39, v48, v49
	v_cvt_pk_bf16_f32 v40, v40, v41
	v_cvt_pk_bf16_f32 v41, v50, v51
	global_store_dwordx4 v[54:55], v[38:41], off offset:256
	v_pk_fma_f32 v[34:35], v[142:143], v[192:193], v[34:35] op_sel_hi:[1,0,1] neg_lo:[1,0,0] neg_hi:[1,0,0]
	v_pk_fma_f32 v[36:37], v[130:131], v[192:193], v[36:37] op_sel_hi:[1,0,1]
	v_pk_fma_f32 v[40:41], v[150:151], v[192:193], v[42:43] op_sel_hi:[1,0,1] neg_lo:[1,0,0] neg_hi:[1,0,0]
	v_pk_fma_f32 v[42:43], v[134:135], v[192:193], v[44:45] op_sel_hi:[1,0,1]
	v_add_u32_e32 v0, 0xf0000, v204
	v_pk_fma_f32 v[42:43], v[192:193], v[42:43], v[148:149] op_sel:[1,0,0]
	v_pk_fma_f32 v[40:41], v[192:193], v[40:41], v[146:147] op_sel:[1,0,0]
	v_pk_fma_f32 v[44:45], v[192:193], v[36:37], v[140:141] op_sel:[1,0,0]
	v_pk_fma_f32 v[36:37], v[192:193], v[34:35], v[138:139] op_sel:[1,0,0]
	v_lshl_add_u64 v[38:39], v[0:1], 1, s[74:75]
	v_cvt_pk_bf16_f32 v34, v40, v41
	v_cvt_pk_bf16_f32 v35, v42, v43
	v_cvt_pk_bf16_f32 v36, v36, v37
	v_cvt_pk_bf16_f32 v37, v44, v45
	v_pk_fma_f32 v[30:31], v[192:193], v[166:167], v[30:31] op_sel_hi:[0,1,1] neg_lo:[1,0,0] neg_hi:[1,0,0]
	v_pk_fma_f32 v[32:33], v[192:193], v[168:169], v[32:33] op_sel_hi:[0,1,1] neg_lo:[1,0,0] neg_hi:[1,0,0]
	v_pk_fma_f32 v[22:23], v[192:193], v[158:159], v[22:23] op_sel_hi:[0,1,1] neg_lo:[1,0,0] neg_hi:[1,0,0]
	v_pk_fma_f32 v[24:25], v[192:193], v[160:161], v[24:25] op_sel_hi:[0,1,1] neg_lo:[1,0,0] neg_hi:[1,0,0]
	global_store_dwordx4 v[38:39], v[34:37], off
	v_pk_fma_f32 v[32:33], v[192:193], v[32:33], v[164:165] op_sel:[1,0,0]
	v_pk_fma_f32 v[30:31], v[192:193], v[30:31], v[162:163] op_sel:[1,0,0]
	v_pk_fma_f32 v[34:35], v[192:193], v[24:25], v[156:157] op_sel:[1,0,0]
	v_pk_fma_f32 v[24:25], v[192:193], v[22:23], v[154:155] op_sel:[1,0,0]
	v_cvt_pk_bf16_f32 v22, v30, v31
	v_cvt_pk_bf16_f32 v23, v32, v33
	v_cvt_pk_bf16_f32 v24, v24, v25
	v_cvt_pk_bf16_f32 v25, v34, v35
	global_store_dwordx4 v[38:39], v[22:25], off offset:256
	v_pk_fma_f32 v[18:19], v[142:143], v[190:191], v[18:19] op_sel_hi:[1,0,1] neg_lo:[1,0,0] neg_hi:[1,0,0]
	v_pk_fma_f32 v[20:21], v[130:131], v[190:191], v[20:21] op_sel_hi:[1,0,1]
	v_pk_fma_f32 v[24:25], v[150:151], v[190:191], v[26:27] op_sel_hi:[1,0,1] neg_lo:[1,0,0] neg_hi:[1,0,0]
	v_pk_fma_f32 v[26:27], v[134:135], v[190:191], v[28:29] op_sel_hi:[1,0,1]
	v_add_u32_e32 v0, 0x108000, v204
	v_pk_fma_f32 v[26:27], v[190:191], v[26:27], v[148:149] op_sel:[1,0,0]
	v_pk_fma_f32 v[24:25], v[190:191], v[24:25], v[146:147] op_sel:[1,0,0]
	v_pk_fma_f32 v[28:29], v[190:191], v[20:21], v[140:141] op_sel:[1,0,0]
	v_pk_fma_f32 v[20:21], v[190:191], v[18:19], v[138:139] op_sel:[1,0,0]
	v_lshl_add_u64 v[22:23], v[0:1], 1, s[74:75]
	v_cvt_pk_bf16_f32 v18, v24, v25
	v_cvt_pk_bf16_f32 v19, v26, v27
	v_cvt_pk_bf16_f32 v20, v20, v21
	v_cvt_pk_bf16_f32 v21, v28, v29
	v_pk_fma_f32 v[14:15], v[190:191], v[166:167], v[14:15] op_sel_hi:[0,1,1] neg_lo:[1,0,0] neg_hi:[1,0,0]
	v_pk_fma_f32 v[16:17], v[190:191], v[168:169], v[16:17] op_sel_hi:[0,1,1] neg_lo:[1,0,0] neg_hi:[1,0,0]
	v_pk_fma_f32 v[10:11], v[190:191], v[158:159], v[10:11] op_sel_hi:[0,1,1] neg_lo:[1,0,0] neg_hi:[1,0,0]
	v_pk_fma_f32 v[12:13], v[190:191], v[160:161], v[12:13] op_sel_hi:[0,1,1] neg_lo:[1,0,0] neg_hi:[1,0,0]
	global_store_dwordx4 v[22:23], v[18:21], off
	v_pk_fma_f32 v[16:17], v[190:191], v[16:17], v[164:165] op_sel:[1,0,0]
	v_pk_fma_f32 v[14:15], v[190:191], v[14:15], v[162:163] op_sel:[1,0,0]
	v_pk_fma_f32 v[18:19], v[190:191], v[12:13], v[156:157] op_sel:[1,0,0]
	v_pk_fma_f32 v[12:13], v[190:191], v[10:11], v[154:155] op_sel:[1,0,0]
	v_cvt_pk_bf16_f32 v10, v14, v15
	v_cvt_pk_bf16_f32 v11, v16, v17
	v_cvt_pk_bf16_f32 v12, v12, v13
	v_cvt_pk_bf16_f32 v13, v18, v19
	global_store_dwordx4 v[22:23], v[10:13], off offset:256
	s_andn2_b64 vcc, exec, s[6:7]
	s_mov_b64 s[6:7], -1
	s_cbranch_vccnz .LBB0_572
	s_mov_b32 s98, 1
.LBB0_591:
	s_mov_b64 s[6:7], exec
	v_readlane_b32 s0, v254, 48
	v_readlane_b32 s1, v254, 49
	s_and_b64 s[0:1], s[6:7], s[0:1]
	s_mov_b64 exec, s[0:1]
	s_cbranch_execz .LBB0_593
	v_readlane_b32 s0, v254, 52
	v_lshl_add_u32 v0, s16, 11, v175
	v_readlane_b32 s1, v254, 53
	s_nop 0
	v_lshl_add_u64 v[6:7], v[0:1], 2, s[0:1]
	global_load_dwordx4 v[2:5], v[6:7], off offset:16
	s_nop 0
	global_load_dwordx4 v[6:9], v[6:7], off

; #define PG8_STAGE(bufoff, gbase, voff) do { _Pragma("unroll") for (int _i = 0; _i < 2; ++_i) \
;         __builtin_amdgcn_global_load_lds((const unsigned*)((const char*)(gbase) + (voff)[_i]), (PG8_LAS unsigned*)(lds + (bufoff) + ldsw + _i * 8192), 16, 0, 0); } while (0)
; #define PG8_LDA(dst, b, h) do { _Pragma("unroll") for (int m = 0; m < 4; ++m) _Pragma("unroll") for (int k = 0; k < 2; ++k) dst[m][k] = *(const PG8_LAS bf16x8*)(lds + PG8_SA(b, h) + aoff + m * 2048 + k * 1024); } while (0)
; #define PG8_LDB(dst, b, h) do { _Pragma("unroll") for (int n = 0; n < 2; ++n) _Pragma("unroll") for (int k = 0; k < 2; ++k) dst[n][k] = *(const PG8_LAS bf16x8*)(lds + PG8_SB(b, h) + boff + n * 2048 + k * 1024); } while (0)
; #define PG8_MMA(ai, bj, At, Bt) do { __builtin_amdgcn_s_setprio(1); _Pragma("unroll") for (int m = 0; m < 4; ++m) _Pragma("unroll") for (int n = 0; n < 2; ++n) _Pragma("unroll") for (int k = 0; k < 2; ++k) \
;         acc[ai][bj][m][n] = __builtin_amdgcn_mfma_f32_16x16x32_bf16(Bt[n][k], At[m][k], acc[ai][bj][m][n], 0, 0, 0); __builtin_amdgcn_s_setprio(0); } while (0)
; #define PG8_WAIT_V(n) asm volatile("s_waitcnt vmcnt(" #n ")" ::: "memory")
; #define PG8_WAIT_L(n) asm volatile("s_waitcnt lgkmcnt(" #n ")" ::: "memory")
; #define PG8_BAR __builtin_amdgcn_s_barrier()
; template <class Epi, class Sched, bool ALIGN_EPI = false, bool SP2 = false>
; __device__ __forceinline__ void gemm_phase(PG8_LAS unsigned char* lds, const Gemm g, const Sched& S, const Epi& E, const int wave_id) {
;     ...
;             const char* a1 = cA + (size_t)(t + 1) * kstep;
;             const char* a2 = last ? nA : cA + (size_t)(t + 2) * kstep; const char* b2 = last ? nB : cB + (size_t)(t + 2) * kstep;
;             const char* a3 = a2 + kstep; const char* b3 = b2 + kstep;
;             if (last && has_next) S.a_ready(nxt);
;             if constexpr (SP2) {
;             PG8_LDB(B0, 0, 0); PG8_LDB(B1, 0, 1); PG8_SCHED; PG8_LDA(At, 0, 0); PG8_STAGE(PG8_SA(1, 1), a1 + hstepA, voffA);
;             PG8_WAIT_V(8); PG8_WAIT_L(0); PG8_BAR; PG8_MMA(0, 0, At, B0); PG8_MMA(0, 1, At, B1); PG8_BAR; PG8_SCHED;
;             PG8_LDA(At, 0, 1); PG8_STAGE(PG8_SB(0, 0), b2, voffB); PG8_STAGE(PG8_SB(0, 1), b2 + hstepB, voffB); PG8_STAGE(PG8_SA(0, 0), a2, voffA);
;             PG8_WAIT_V(8); PG8_WAIT_L(0); PG8_BAR; PG8_MMA(1, 0, At, B0); PG8_MMA(1, 1, At, B1); PG8_BAR; PG8_SCHED;
.LBB0_627:
	s_add_u32 s26, s8, 0xfffc0080
	s_addc_u32 s27, s9, -1
	s_add_i32 s38, 0, 0x10000
	s_cmp_eq_u32 s37, 12
	s_cselect_b32 s29, s17, s27
	s_cselect_b32 s28, s25, s26
	v_add_u32_e32 v0, s38, v240
	s_cselect_b32 s27, s15, vcc_hi
	s_cselect_b32 s26, s50, vcc_lo
	s_add_i32 s0, 0, 0x14000
	ds_read_b128 v[114:117], v0
	ds_read_b128 v[118:121], v0 offset:1024
	ds_read_b128 v[122:125], v0 offset:2048
	ds_read_b128 v[130:133], v0 offset:3072
	v_add_u32_e32 v0, s0, v240
	ds_read_b128 v[138:141], v0
	ds_read_b128 v[142:145], v0 offset:1024
	ds_read_b128 v[150:153], v0 offset:2048
	ds_read_b128 v[154:157], v0 offset:3072
	v_lshl_add_u64 v[198:199], s[8:9], 0, v[186:187]
	s_add_i32 m0, s30, 0xc000
	ds_read_b128 v[190:193], v245
	ds_read_b128 v[194:197], v245 offset:1024
	ds_read_b128 v[202:205], v245 offset:2048
	ds_read_b128 v[206:209], v245 offset:3072
	ds_read_b128 v[210:213], v245 offset:4096
	ds_read_b128 v[214:217], v245 offset:5120
	ds_read_b128 v[218:221], v245 offset:6144
	ds_read_b128 v[222:225], v245 offset:7168
	global_load_lds_dwordx4 v[198:199], off
	v_lshl_add_u64 v[198:199], s[8:9], 0, v[188:189]
	s_add_i32 m0, s30, 0xe000
	s_nop 0
	global_load_lds_dwordx4 v[198:199], off
	s_waitcnt vmcnt(24)
	s_cmp_eq_u32 s98, 1
	s_cbranch_scc1 .Lrw_5
	s_waitcnt vmcnt(8)
.Lrw_5:
	s_waitcnt lgkmcnt(0)
	s_barrier
	s_setprio 1
	s_waitcnt lgkmcnt(0)
	v_mfma_f32_16x16x32_bf16 v[166:169], v[114:117], v[190:193], v[166:169]
	v_mfma_f32_16x16x32_bf16 v[162:165], v[122:125], v[190:193], v[162:165]
	v_mfma_f32_16x16x32_bf16 v[134:137], v[114:117], v[202:205], v[134:137]
	v_mfma_f32_16x16x32_bf16 v[126:129], v[122:125], v[202:205], v[126:129]
	v_mfma_f32_16x16x32_bf16 v[102:105], v[114:117], v[210:213], v[102:105]
	v_mfma_f32_16x16x32_bf16 v[98:101], v[122:125], v[210:213], v[98:101]
	v_mfma_f32_16x16x32_bf16 v[86:89], v[114:117], v[218:221], v[86:89]
	v_mfma_f32_16x16x32_bf16 v[82:85], v[122:125], v[218:221], v[82:85]
	v_mfma_f32_16x16x32_bf16 v[166:169], v[118:121], v[194:197], v[166:169]
	v_mfma_f32_16x16x32_bf16 v[162:165], v[130:133], v[194:197], v[162:165]
	v_mfma_f32_16x16x32_bf16 v[134:137], v[118:121], v[206:209], v[134:137]
	v_mfma_f32_16x16x32_bf16 v[126:129], v[130:133], v[206:209], v[126:129]
	v_mfma_f32_16x16x32_bf16 v[102:105], v[118:121], v[214:217], v[102:105]
	v_mfma_f32_16x16x32_bf16 v[98:101], v[130:133], v[214:217], v[98:101]
	v_mfma_f32_16x16x32_bf16 v[86:89], v[118:121], v[222:225], v[86:89]
	v_mfma_f32_16x16x32_bf16 v[82:85], v[130:133], v[222:225], v[82:85]
	s_setprio 0
	s_setprio 1
	v_mfma_f32_16x16x32_bf16 v[158:161], v[138:141], v[190:193], v[158:161]
	v_mfma_f32_16x16x32_bf16 v[146:149], v[150:153], v[190:193], v[146:149]
	v_mfma_f32_16x16x32_bf16 v[110:113], v[138:141], v[202:205], v[110:113]
	v_mfma_f32_16x16x32_bf16 v[106:109], v[150:153], v[202:205], v[106:109]
	v_mfma_f32_16x16x32_bf16 v[94:97], v[138:141], v[210:213], v[94:97]
	v_mfma_f32_16x16x32_bf16 v[90:93], v[150:153], v[210:213], v[90:93]
	v_mfma_f32_16x16x32_bf16 v[78:81], v[138:141], v[218:221], v[78:81]
	v_mfma_f32_16x16x32_bf16 v[74:77], v[150:153], v[218:221], v[74:77]
	v_mfma_f32_16x16x32_bf16 v[158:161], v[142:145], v[194:197], v[158:161]
	v_mfma_f32_16x16x32_bf16 v[146:149], v[154:157], v[194:197], v[146:149]
	v_mfma_f32_16x16x32_bf16 v[110:113], v[142:145], v[206:209], v[110:113]
	v_mfma_f32_16x16x32_bf16 v[106:109], v[154:157], v[206:209], v[106:109]
	v_mfma_f32_16x16x32_bf16 v[94:97], v[142:145], v[214:217], v[94:97]
	v_mfma_f32_16x16x32_bf16 v[90:93], v[154:157], v[214:217], v[90:93]
	v_mfma_f32_16x16x32_bf16 v[78:81], v[142:145], v[222:225], v[78:81]
	v_mfma_f32_16x16x32_bf16 v[74:77], v[154:157], v[222:225], v[74:77]
	s_setprio 0
	s_barrier
	s_add_i32 s1, s38, s23
	v_lshl_add_u64 v[198:199], s[26:27], 0, v[180:181]
	s_mov_b32 m0, s1
	ds_read_b128 v[190:193], v245 offset:16384
	ds_read_b128 v[194:197], v245 offset:17408
	ds_read_b128 v[202:205], v245 offset:18432
	ds_read_b128 v[206:209], v245 offset:19456
	ds_read_b128 v[210:213], v245 offset:20480
	ds_read_b128 v[214:217], v245 offset:21504
	ds_read_b128 v[218:221], v245 offset:22528
	ds_read_b128 v[222:225], v245 offset:23552
	global_load_lds_dwordx4 v[198:199], off
	s_add_i32 m0, s1, 0x2000
	s_add_u32 s38, s26, 0x40000
	v_lshl_add_u64 v[234:235], s[26:27], 0, v[184:185]
	s_addc_u32 s39, s27, 0
	s_add_i32 s0, s0, s23
	global_load_lds_dwordx4 v[234:235], off
	v_lshl_add_u64 v[236:237], s[38:39], 0, v[180:181]
	s_mov_b32 m0, s0
	v_lshl_add_u64 v[246:247], s[28:29], 0, v[182:183]
	global_load_lds_dwordx4 v[236:237], off
	v_lshl_add_u64 v[236:237], s[38:39], 0, v[184:185]
	s_add_i32 m0, s0, 0x2000
	s_nop 0
	global_load_lds_dwordx4 v[236:237], off
	v_lshl_add_u64 v[236:237], s[28:29], 0, v[178:179]
	s_mov_b32 m0, s30
	s_nop 0
	global_load_lds_dwordx4 v[236:237], off
	s_mov_b32 m0, s31
	s_nop 0
	global_load_lds_dwordx4 v[246:247], off
	s_waitcnt vmcnt(24)
	s_cmp_eq_u32 s98, 1
	s_cbranch_scc1 .Lrw_6
	s_waitcnt vmcnt(8)
; #define PG8_STAGE(bufoff, gbase, voff) do { _Pragma("unroll") for (int _i = 0; _i < 2; ++_i) \
;         __builtin_amdgcn_global_load_lds((const unsigned*)((const char*)(gbase) + (voff)[_i]), (PG8_LAS unsigned*)(lds + (bufoff) + ldsw + _i * 8192), 16, 0, 0); } while (0)
; #define PG8_LDA(dst, b, h) do { _Pragma("unroll") for (int m = 0; m < 4; ++m) _Pragma("unroll") for (int k = 0; k < 2; ++k) dst[m][k] = *(const PG8_LAS bf16x8*)(lds + PG8_SA(b, h) + aoff + m * 2048 + k * 1024); } while (0)
; #define PG8_LDB(dst, b, h) do { _Pragma("unroll") for (int n = 0; n < 2; ++n) _Pragma("unroll") for (int k = 0; k < 2; ++k) dst[n][k] = *(const PG8_LAS bf16x8*)(lds + PG8_SB(b, h) + boff + n * 2048 + k * 1024); } while (0)
; #define PG8_MMA(ai, bj, At, Bt) do { __builtin_amdgcn_s_setprio(1); _Pragma("unroll") for (int m = 0; m < 4; ++m) _Pragma("unroll") for (int n = 0; n < 2; ++n) _Pragma("unroll") for (int k = 0; k < 2; ++k) \
;         acc[ai][bj][m][n] = __builtin_amdgcn_mfma_f32_16x16x32_bf16(Bt[n][k], At[m][k], acc[ai][bj][m][n], 0, 0, 0); __builtin_amdgcn_s_setprio(0); } while (0)
; #define PG8_WAIT_V(n) asm volatile("s_waitcnt vmcnt(" #n ")" ::: "memory")
; #define PG8_WAIT_L(n) asm volatile("s_waitcnt lgkmcnt(" #n ")" ::: "memory")
; #define PG8_BAR __builtin_amdgcn_s_barrier()
; #define PG8_SCHED __builtin_amdgcn_sched_barrier(0)
; template <class Epi, class Sched, bool ALIGN_EPI = false, bool SP2 = false>
; __device__ __forceinline__ void gemm_phase(PG8_LAS unsigned char* lds, const Gemm g, const Sched& S, const Epi& E, const int wave_id) {
;     ...
;             PG8_WAIT_V(8); PG8_WAIT_L(0); PG8_BAR; PG8_MMA(1, 0, At, B0); PG8_MMA(1, 1, At, B1); PG8_BAR; PG8_SCHED;
;             PG8_LDB(B0, 1, 0); PG8_LDB(B1, 1, 1); PG8_SCHED; PG8_LDA(At, 1, 0); PG8_STAGE(PG8_SA(0, 1), a2 + hstepA, voffA);
;             PG8_WAIT_V(8); PG8_WAIT_L(0); PG8_BAR; PG8_MMA(0, 0, At, B0); PG8_MMA(0, 1, At, B1); PG8_BAR; PG8_SCHED;
.Lrw_6:
	s_mov_b32 s98, 0
	s_waitcnt lgkmcnt(0)
	s_barrier
	s_setprio 1
	s_waitcnt lgkmcnt(0)
	v_mfma_f32_16x16x32_bf16 v[70:73], v[114:117], v[190:193], v[70:73]
	v_mfma_f32_16x16x32_bf16 v[66:69], v[122:125], v[190:193], v[66:69]
	v_mfma_f32_16x16x32_bf16 v[54:57], v[114:117], v[202:205], v[54:57]
	v_mfma_f32_16x16x32_bf16 v[50:53], v[122:125], v[202:205], v[50:53]
	v_mfma_f32_16x16x32_bf16 v[38:41], v[114:117], v[210:213], v[38:41]
	v_mfma_f32_16x16x32_bf16 v[34:37], v[122:125], v[210:213], v[34:37]
	v_mfma_f32_16x16x32_bf16 v[22:25], v[114:117], v[218:221], v[22:25]
	v_mfma_f32_16x16x32_bf16 v[18:21], v[122:125], v[218:221], v[18:21]
	v_mfma_f32_16x16x32_bf16 v[70:73], v[118:121], v[194:197], v[70:73]
	v_mfma_f32_16x16x32_bf16 v[66:69], v[130:133], v[194:197], v[66:69]
	v_mfma_f32_16x16x32_bf16 v[54:57], v[118:121], v[206:209], v[54:57]
	v_mfma_f32_16x16x32_bf16 v[50:53], v[130:133], v[206:209], v[50:53]
	v_mfma_f32_16x16x32_bf16 v[38:41], v[118:121], v[214:217], v[38:41]
	v_mfma_f32_16x16x32_bf16 v[34:37], v[130:133], v[214:217], v[34:37]
	v_mfma_f32_16x16x32_bf16 v[22:25], v[118:121], v[222:225], v[22:25]
	v_mfma_f32_16x16x32_bf16 v[18:21], v[130:133], v[222:225], v[18:21]
	s_setprio 0
	s_setprio 1
	v_mfma_f32_16x16x32_bf16 v[62:65], v[138:141], v[190:193], v[62:65]
	v_mfma_f32_16x16x32_bf16 v[58:61], v[150:153], v[190:193], v[58:61]
	v_mfma_f32_16x16x32_bf16 v[46:49], v[138:141], v[202:205], v[46:49]
	v_mfma_f32_16x16x32_bf16 v[42:45], v[150:153], v[202:205], v[42:45]
	v_mfma_f32_16x16x32_bf16 v[30:33], v[138:141], v[210:213], v[30:33]
	v_mfma_f32_16x16x32_bf16 v[26:29], v[150:153], v[210:213], v[26:29]
	v_mfma_f32_16x16x32_bf16 v[14:17], v[138:141], v[218:221], v[14:17]
	v_mfma_f32_16x16x32_bf16 v[10:13], v[150:153], v[218:221], v[10:13]
	v_mfma_f32_16x16x32_bf16 v[62:65], v[142:145], v[194:197], v[62:65]
	v_mfma_f32_16x16x32_bf16 v[58:61], v[154:157], v[194:197], v[58:61]
	v_mfma_f32_16x16x32_bf16 v[46:49], v[142:145], v[206:209], v[46:49]
	v_mfma_f32_16x16x32_bf16 v[42:45], v[154:157], v[206:209], v[42:45]
	v_mfma_f32_16x16x32_bf16 v[30:33], v[142:145], v[214:217], v[30:33]
	v_mfma_f32_16x16x32_bf16 v[26:29], v[154:157], v[214:217], v[26:29]
	v_mfma_f32_16x16x32_bf16 v[14:17], v[142:145], v[222:225], v[14:17]
	v_mfma_f32_16x16x32_bf16 v[10:13], v[154:157], v[222:225], v[10:13]
	s_setprio 0
	s_barrier
	s_add_i32 s0, 0, 0x18000
	v_add_u32_e32 v0, s0, v240
	s_add_i32 s1, 0, 0x1c000
	ds_read_b128 v[114:117], v0
	ds_read_b128 v[118:121], v0 offset:1024
	ds_read_b128 v[122:125], v0 offset:2048
	ds_read_b128 v[130:133], v0 offset:3072
	v_add_u32_e32 v0, s1, v240
	ds_read_b128 v[138:141], v0
	ds_read_b128 v[142:145], v0 offset:1024
	ds_read_b128 v[150:153], v0 offset:2048
	ds_read_b128 v[154:157], v0 offset:3072
	s_add_u32 s28, s28, 0x40000
	s_addc_u32 s29, s29, 0
	s_mov_b32 m0, s34
	v_lshl_add_u64 v[248:249], s[28:29], 0, v[178:179]
	ds_read_b128 v[190:193], v245 offset:32768
	ds_read_b128 v[194:197], v245 offset:33792
	ds_read_b128 v[202:205], v245 offset:34816
	ds_read_b128 v[206:209], v245 offset:35840
	ds_read_b128 v[210:213], v245 offset:36864
	ds_read_b128 v[214:217], v245 offset:37888
	ds_read_b128 v[218:221], v245 offset:38912
	ds_read_b128 v[222:225], v245 offset:39936
	global_load_lds_dwordx4 v[248:249], off
	v_lshl_add_u64 v[248:249], s[28:29], 0, v[182:183]
	s_mov_b32 m0, s35
	s_nop 0
	global_load_lds_dwordx4 v[248:249], off
	s_waitcnt vmcnt(8)
	s_waitcnt lgkmcnt(0)
	s_barrier
	s_setprio 1
	s_waitcnt lgkmcnt(0)
	v_mfma_f32_16x16x32_bf16 v[166:169], v[114:117], v[190:193], v[166:169]
	v_mfma_f32_16x16x32_bf16 v[162:165], v[122:125], v[190:193], v[162:165]
	v_mfma_f32_16x16x32_bf16 v[134:137], v[114:117], v[202:205], v[134:137]
	v_mfma_f32_16x16x32_bf16 v[126:129], v[122:125], v[202:205], v[126:129]
	v_mfma_f32_16x16x32_bf16 v[102:105], v[114:117], v[210:213], v[102:105]
	v_mfma_f32_16x16x32_bf16 v[98:101], v[122:125], v[210:213], v[98:101]
	v_mfma_f32_16x16x32_bf16 v[86:89], v[114:117], v[218:221], v[86:89]
	v_mfma_f32_16x16x32_bf16 v[82:85], v[122:125], v[218:221], v[82:85]
	v_mfma_f32_16x16x32_bf16 v[166:169], v[118:121], v[194:197], v[166:169]
	v_mfma_f32_16x16x32_bf16 v[162:165], v[130:133], v[194:197], v[162:165]
	v_mfma_f32_16x16x32_bf16 v[134:137], v[118:121], v[206:209], v[134:137]
	v_mfma_f32_16x16x32_bf16 v[126:129], v[130:133], v[206:209], v[126:129]
	v_mfma_f32_16x16x32_bf16 v[102:105], v[118:121], v[214:217], v[102:105]
	v_mfma_f32_16x16x32_bf16 v[98:101], v[130:133], v[214:217], v[98:101]
	v_mfma_f32_16x16x32_bf16 v[86:89], v[118:121], v[222:225], v[86:89]
	v_mfma_f32_16x16x32_bf16 v[82:85], v[130:133], v[222:225], v[82:85]
	s_setprio 0
	s_setprio 1
	v_mfma_f32_16x16x32_bf16 v[158:161], v[138:141], v[190:193], v[158:161]
	v_mfma_f32_16x16x32_bf16 v[146:149], v[150:153], v[190:193], v[146:149]
	v_mfma_f32_16x16x32_bf16 v[110:113], v[138:141], v[202:205], v[110:113]
	v_mfma_f32_16x16x32_bf16 v[106:109], v[150:153], v[202:205], v[106:109]
	v_mfma_f32_16x16x32_bf16 v[94:97], v[138:141], v[210:213], v[94:97]
	v_mfma_f32_16x16x32_bf16 v[90:93], v[150:153], v[210:213], v[90:93]
	v_mfma_f32_16x16x32_bf16 v[78:81], v[138:141], v[218:221], v[78:81]
	v_mfma_f32_16x16x32_bf16 v[74:77], v[150:153], v[218:221], v[74:77]
	v_mfma_f32_16x16x32_bf16 v[158:161], v[142:145], v[194:197], v[158:161]
	v_mfma_f32_16x16x32_bf16 v[146:149], v[154:157], v[194:197], v[146:149]
	v_mfma_f32_16x16x32_bf16 v[110:113], v[142:145], v[206:209], v[110:113]
	v_mfma_f32_16x16x32_bf16 v[106:109], v[154:157], v[206:209], v[106:109]
	v_mfma_f32_16x16x32_bf16 v[94:97], v[142:145], v[214:217], v[94:97]
	v_mfma_f32_16x16x32_bf16 v[90:93], v[154:157], v[214:217], v[90:93]
	v_mfma_f32_16x16x32_bf16 v[78:81], v[142:145], v[222:225], v[78:81]
	v_mfma_f32_16x16x32_bf16 v[74:77], v[154:157], v[222:225], v[74:77]
	s_setprio 0
	s_barrier
; #define PG8_STAGE(bufoff, gbase, voff) do { _Pragma("unroll") for (int _i = 0; _i < 2; ++_i) \
;         __builtin_amdgcn_global_load_lds((const unsigned*)((const char*)(gbase) + (voff)[_i]), (PG8_LAS unsigned*)(lds + (bufoff) + ldsw + _i * 8192), 16, 0, 0); } while (0)
; #define PG8_LDA(dst, b, h) do { _Pragma("unroll") for (int m = 0; m < 4; ++m) _Pragma("unroll") for (int k = 0; k < 2; ++k) dst[m][k] = *(const PG8_LAS bf16x8*)(lds + PG8_SA(b, h) + aoff + m * 2048 + k * 1024); } while (0)
; #define PG8_MMA(ai, bj, At, Bt) do { __builtin_amdgcn_s_setprio(1); _Pragma("unroll") for (int m = 0; m < 4; ++m) _Pragma("unroll") for (int n = 0; n < 2; ++n) _Pragma("unroll") for (int k = 0; k < 2; ++k) \
;         acc[ai][bj][m][n] = __builtin_amdgcn_mfma_f32_16x16x32_bf16(Bt[n][k], At[m][k], acc[ai][bj][m][n], 0, 0, 0); __builtin_amdgcn_s_setprio(0); } while (0)
; #define PG8_WAIT_V(n) asm volatile("s_waitcnt vmcnt(" #n ")" ::: "memory")
; #define PG8_WAIT_L(n) asm volatile("s_waitcnt lgkmcnt(" #n ")" ::: "memory")
; #define PG8_BAR __builtin_amdgcn_s_barrier()
; #define PG8_SCHED __builtin_amdgcn_sched_barrier(0)
; template <class Epi, class Sched, bool ALIGN_EPI = false, bool SP2 = false>
; __device__ __forceinline__ void gemm_phase(PG8_LAS unsigned char* lds, const Gemm g, const Sched& S, const Epi& E, const int wave_id) {
;     ...
;         for (int t = 0; t < nt; t += 2) {
;             const bool last = (t == nt - 2);
;     ...
;             PG8_LDA(At, 1, 1); PG8_STAGE(PG8_SB(1, 0), b3, voffB); PG8_STAGE(PG8_SB(1, 1), b3 + hstepB, voffB); PG8_STAGE(PG8_SA(1, 0), a3, voffA);
;             PG8_WAIT_V(8); PG8_WAIT_L(0); PG8_BAR; PG8_MMA(1, 0, At, B0); PG8_MMA(1, 1, At, B1); PG8_BAR; PG8_SCHED;
	s_add_i32 s0, s0, s23
	v_lshl_add_u64 v[198:199], v[198:199], 0, s[62:63]
	s_mov_b32 m0, s0
	ds_read_b128 v[190:193], v245 offset:49152
	ds_read_b128 v[194:197], v245 offset:50176
	ds_read_b128 v[202:205], v245 offset:51200
	ds_read_b128 v[206:209], v245 offset:52224
	ds_read_b128 v[210:213], v245 offset:53248
	ds_read_b128 v[214:217], v245 offset:54272
	ds_read_b128 v[218:221], v245 offset:55296
	ds_read_b128 v[222:225], v245 offset:56320
	global_load_lds_dwordx4 v[198:199], off
	s_add_i32 m0, s0, 0x2000
	s_add_u32 s26, s26, 0x40080
	v_lshl_add_u64 v[198:199], v[234:235], 0, s[62:63]
	s_addc_u32 s27, s27, 0
	s_add_i32 s0, s1, s23
	global_load_lds_dwordx4 v[198:199], off
	v_lshl_add_u64 v[198:199], s[26:27], 0, v[180:181]
	s_mov_b32 m0, s0
	s_nop 0
	global_load_lds_dwordx4 v[198:199], off
	v_lshl_add_u64 v[198:199], s[26:27], 0, v[184:185]
	s_add_i32 m0, s0, 0x2000
	s_nop 0
	global_load_lds_dwordx4 v[198:199], off
	v_lshl_add_u64 v[198:199], v[236:237], 0, s[62:63]
	s_mov_b32 m0, s45
	s_nop 0
	global_load_lds_dwordx4 v[198:199], off
	v_lshl_add_u64 v[198:199], v[246:247], 0, s[62:63]
	s_mov_b32 m0, s76
	s_nop 0
	global_load_lds_dwordx4 v[198:199], off
	s_waitcnt vmcnt(8)
	s_waitcnt lgkmcnt(0)
	s_barrier
	s_setprio 1
	s_waitcnt lgkmcnt(0)
	v_mfma_f32_16x16x32_bf16 v[70:73], v[114:117], v[190:193], v[70:73]
	v_mfma_f32_16x16x32_bf16 v[66:69], v[122:125], v[190:193], v[66:69]
	v_mfma_f32_16x16x32_bf16 v[54:57], v[114:117], v[202:205], v[54:57]
	v_mfma_f32_16x16x32_bf16 v[50:53], v[122:125], v[202:205], v[50:53]
	v_mfma_f32_16x16x32_bf16 v[38:41], v[114:117], v[210:213], v[38:41]
	v_mfma_f32_16x16x32_bf16 v[34:37], v[122:125], v[210:213], v[34:37]
	v_mfma_f32_16x16x32_bf16 v[22:25], v[114:117], v[218:221], v[22:25]
	v_mfma_f32_16x16x32_bf16 v[18:21], v[122:125], v[218:221], v[18:21]
	v_mfma_f32_16x16x32_bf16 v[70:73], v[118:121], v[194:197], v[70:73]
	v_mfma_f32_16x16x32_bf16 v[66:69], v[130:133], v[194:197], v[66:69]
	v_mfma_f32_16x16x32_bf16 v[54:57], v[118:121], v[206:209], v[54:57]
	v_mfma_f32_16x16x32_bf16 v[50:53], v[130:133], v[206:209], v[50:53]
	v_mfma_f32_16x16x32_bf16 v[38:41], v[118:121], v[214:217], v[38:41]
	v_mfma_f32_16x16x32_bf16 v[34:37], v[130:133], v[214:217], v[34:37]
	v_mfma_f32_16x16x32_bf16 v[22:25], v[118:121], v[222:225], v[22:25]
	v_mfma_f32_16x16x32_bf16 v[18:21], v[130:133], v[222:225], v[18:21]
	s_setprio 0
	s_setprio 1
	v_mfma_f32_16x16x32_bf16 v[62:65], v[138:141], v[190:193], v[62:65]
	v_mfma_f32_16x16x32_bf16 v[58:61], v[150:153], v[190:193], v[58:61]
	v_mfma_f32_16x16x32_bf16 v[46:49], v[138:141], v[202:205], v[46:49]
	v_mfma_f32_16x16x32_bf16 v[42:45], v[150:153], v[202:205], v[42:45]
	v_mfma_f32_16x16x32_bf16 v[30:33], v[138:141], v[210:213], v[30:33]
	v_mfma_f32_16x16x32_bf16 v[26:29], v[150:153], v[210:213], v[26:29]
	v_mfma_f32_16x16x32_bf16 v[14:17], v[138:141], v[218:221], v[14:17]
	v_mfma_f32_16x16x32_bf16 v[10:13], v[150:153], v[218:221], v[10:13]
	v_mfma_f32_16x16x32_bf16 v[62:65], v[142:145], v[194:197], v[62:65]
	v_mfma_f32_16x16x32_bf16 v[58:61], v[154:157], v[194:197], v[58:61]
	v_mfma_f32_16x16x32_bf16 v[46:49], v[142:145], v[206:209], v[46:49]
	v_mfma_f32_16x16x32_bf16 v[42:45], v[154:157], v[206:209], v[42:45]
	v_mfma_f32_16x16x32_bf16 v[30:33], v[142:145], v[214:217], v[30:33]
	v_mfma_f32_16x16x32_bf16 v[26:29], v[154:157], v[214:217], v[26:29]
	v_mfma_f32_16x16x32_bf16 v[14:17], v[142:145], v[222:225], v[14:17]
	v_mfma_f32_16x16x32_bf16 v[10:13], v[154:157], v[222:225], v[10:13]
	s_setprio 0
	s_barrier
	s_add_i32 s37, s37, 2
	s_add_u32 s8, s8, 0x100
	s_addc_u32 s9, s9, 0
	s_add_u32 vcc_lo, vcc_lo, 0x100
	s_addc_u32 vcc_hi, vcc_hi, 0
	s_cmp_gt_u32 s37, 13
	s_cbranch_scc0 .LBB0_627
	s_and_b64 vcc, exec, s[12:13]
	s_cbranch_vccz .LBB0_630
	s_barrier

; template <class Epi, class Sched, bool ALIGN_EPI = false, bool SP2 = false>
; __device__ __forceinline__ void gemm_phase(PG8_LAS unsigned char* lds, const Gemm g, const Sched& S, const Epi& E, const int wave_id) {
;     ...
;         if (!has_next) break;
; #pragma unroll
;         for (int a = 0; a < 2; ++a)
; #pragma unroll
;             for (int b = 0; b < 2; ++b)
; #pragma unroll
;                 for (int m = 0; m < 4; ++m)
; #pragma unroll
;                     for (int n = 0; n < 2; ++n) acc[a][b][m][n] = (f32x4){0.f, 0.f, 0.f, 0.f};
;         cur = nxt; cA = nA; cB = nB; ++ui;
;         if constexpr (Epi::HAS_PF) E.prefetch(cur, tid);
.LBB0_675:
	s_andn2_b64 vcc, exec, s[6:7]
	s_mov_b64 s[6:7], -1
	s_cbranch_vccnz .LBB0_623
	s_mov_b32 s98, 1
	s_and_saveexec_b64 s[6:7], s[80:81]
	s_cbranch_execz .LBB0_678
	v_readlane_b32 s0, v254, 52
	v_lshl_add_u32 v0, s16, 11, v175
	v_readlane_b32 s1, v254, 53
	s_nop 0
	v_lshl_add_u64 v[6:7], v[0:1], 2, s[0:1]
	global_load_dwordx4 v[2:5], v[6:7], off offset:16
	s_nop 0
	global_load_dwordx4 v[6:9], v[6:7], off

; __global__ void __launch_bounds__(512, 2) fwd_megakernel(Args a) {
;     extern __shared__ __attribute__((aligned(16))) unsigned char lds[];
	.amdhsa_kernel _Z14fwd_megakernel4Args
		.amdhsa_group_segment_fixed_size 0
		.amdhsa_private_segment_fixed_size 0
		.amdhsa_kernarg_size 464
		.amdhsa_user_sgpr_count 2
		.amdhsa_user_sgpr_dispatch_ptr 0
		.amdhsa_user_sgpr_queue_ptr 0
		.amdhsa_user_sgpr_kernarg_segment_ptr 1
		.amdhsa_user_sgpr_dispatch_id 0
		.amdhsa_user_sgpr_kernarg_preload_length 0
		.amdhsa_user_sgpr_kernarg_preload_offset 0
		.amdhsa_user_sgpr_private_segment_size 0
		.amdhsa_uses_dynamic_stack 0
		.amdhsa_enable_private_segment 0
		.amdhsa_system_sgpr_workgroup_id_x 1
		.amdhsa_system_sgpr_workgroup_id_y 0
		.amdhsa_system_sgpr_workgroup_id_z 0
		.amdhsa_system_sgpr_workgroup_info 0
		.amdhsa_system_vgpr_workitem_id 2
		.amdhsa_next_free_vgpr 256
		.amdhsa_next_free_sgpr 102
		.amdhsa_accum_offset 256
		.amdhsa_reserve_vcc 1
		.amdhsa_float_round_mode_32 0
		.amdhsa_float_round_mode_16_64 0
		.amdhsa_float_denorm_mode_32 3
		.amdhsa_float_denorm_mode_16_64 3
		.amdhsa_dx10_clamp 1
		.amdhsa_ieee_mode 1
		.amdhsa_fp16_overflow 0
		.amdhsa_tg_split 0
		.amdhsa_exception_fp_ieee_invalid_op 0
		.amdhsa_exception_fp_denorm_src 0
		.amdhsa_exception_fp_ieee_div_zero 0
		.amdhsa_exception_fp_ieee_overflow 0
		.amdhsa_exception_fp_ieee_underflow 0
		.amdhsa_exception_fp_ieee_inexact 0
		.amdhsa_exception_int_div_zero 0
	.end_amdhsa_kernel

; __global__ void __launch_bounds__(512, 2) fwd_megakernel(Args a) {
;     extern __shared__ __attribute__((aligned(16))) unsigned char lds[];
amdhsa.kernels:
  - .agpr_count:     0
    .args:
      - .offset:         0
        .size:           208
        .value_kind:     by_value
      - .offset:         208
        .size:           4
        .value_kind:     hidden_block_count_x
      - .offset:         212
        .size:           4
        .value_kind:     hidden_block_count_y
      - .offset:         216
        .size:           4
        .value_kind:     hidden_block_count_z
      - .offset:         220
        .size:           2
        .value_kind:     hidden_group_size_x
      - .offset:         222
        .size:           2
        .value_kind:     hidden_group_size_y
      - .offset:         224
        .size:           2
        .value_kind:     hidden_group_size_z
      - .offset:         226
        .size:           2
        .value_kind:     hidden_remainder_x
      - .offset:         228
        .size:           2
        .value_kind:     hidden_remainder_y
      - .offset:         230
        .size:           2
        .value_kind:     hidden_remainder_z
      - .offset:         248
        .size:           8
        .value_kind:     hidden_global_offset_x
      - .offset:         256
        .size:           8
        .value_kind:     hidden_global_offset_y
      - .offset:         264
        .size:           8
        .value_kind:     hidden_global_offset_z
      - .offset:         272
        .size:           2
        .value_kind:     hidden_grid_dims
      - .offset:         296
        .size:           8
        .value_kind:     hidden_multigrid_sync_arg
      - .offset:         328
        .size:           4
        .value_kind:     hidden_dynamic_lds_size
    .group_segment_fixed_size: 0
    .kernarg_segment_align: 8
    .kernarg_segment_size: 464
    .language:       OpenCL C
    .language_version:
      - 2
      - 0
    .max_flat_workgroup_size: 512
    .name:           _Z14fwd_megakernel4Args
    .private_segment_fixed_size: 0
    .sgpr_count:     108
    .sgpr_spill_count: 214
    .symbol:         _Z14fwd_megakernel4Args.kd
    .uniform_work_group_size: 1
    .uses_dynamic_stack: false
    .vgpr_count:     256
    .vgpr_spill_count: 0
    .wavefront_size: 64
